# RWKV scan: two rows packed per pk register (no x+y adds), dot/y as 4-op fma chains; LRU conv4 stage batched (4 LDS round trips instead of 32)
# speedup vs baseline: 1.0427x; 1.0077x over previous
.LBB0_283:
	v_and_b32_e32 v39, 63, v132
	v_lshlrev_b32_e32 v0, 2, v132
	v_and_b32_e32 v37, 0xffffff00, v0
	v_lshlrev_b32_e32 v2, 2, v39
	v_add3_u32 v0, 0, v37, v2
	v_ashrrev_i32_e32 v40, 6, v132
	s_add_i32 s24, 0, 0x10000
	s_movk_i32 s25, 0x90
	ds_read2st64_b32 v[154:155], v0 offset0:0 offset1:1
	ds_read2st64_b32 v[156:157], v0 offset0:2 offset1:3
	ds_read2st64_b32 v[158:159], v0 offset0:8 offset1:9
	ds_read2st64_b32 v[160:161], v0 offset0:10 offset1:11
	ds_read2st64_b32 v[162:163], v0 offset0:16 offset1:17
	ds_read2st64_b32 v[164:165], v0 offset0:18 offset1:19
	ds_read2st64_b32 v[166:167], v0 offset0:24 offset1:25
	ds_read2st64_b32 v[168:169], v0 offset0:26 offset1:27
	v_mul_lo_u32 v40, v40, s25
	v_lshlrev_b32_e32 v39, 1, v39
	v_add3_u32 v3, s24, v37, v2
	v_add3_u32 v38, s65, v40, v39
	s_add_i32 s25, 0, 0x14000
	s_andn2_b64 vcc, exec, s[46:47]
	s_waitcnt lgkmcnt(0)
	v_fma_f32 v136, v42, v154, v122
	v_fma_f32 v137, v42, v158, v122
	v_fma_f32 v138, v42, v162, v122
	v_fma_f32 v139, v42, v166, v122
	v_fmac_f32_e32 v136, v43, v155
	v_fmac_f32_e32 v137, v43, v159
	v_fmac_f32_e32 v138, v43, v163
	v_fmac_f32_e32 v139, v43, v167
	v_fmac_f32_e32 v136, v44, v156
	v_fmac_f32_e32 v137, v44, v160
	v_fmac_f32_e32 v138, v44, v164
	v_fmac_f32_e32 v139, v44, v168
	v_fmac_f32_e32 v136, v45, v157
	v_fmac_f32_e32 v137, v45, v161
	v_fmac_f32_e32 v138, v45, v165
	v_fmac_f32_e32 v139, v45, v169
	ds_read2st64_b32 v[154:155], v0 offset0:32 offset1:33
	ds_read2st64_b32 v[156:157], v0 offset0:34 offset1:35
	ds_read2st64_b32 v[158:159], v0 offset0:40 offset1:41
	ds_read2st64_b32 v[160:161], v0 offset0:42 offset1:43
	ds_read2st64_b32 v[162:163], v0 offset0:48 offset1:49
	ds_read2st64_b32 v[164:165], v0 offset0:50 offset1:51
	ds_read2st64_b32 v[166:167], v0 offset0:56 offset1:57
	ds_read2st64_b32 v[168:169], v0 offset0:58 offset1:59
	v_bfe_u32 v140, v136, 16, 1
	v_bfe_u32 v141, v137, 16, 1
	v_bfe_u32 v142, v138, 16, 1
	v_bfe_u32 v143, v139, 16, 1
	v_add3_u32 v140, v136, v140, s97
	v_add3_u32 v141, v137, v141, s97
	v_add3_u32 v142, v138, v142, s97
	v_add3_u32 v143, v139, v143, s97
	ds_write_b32 v3, v136 offset:0
	ds_write_b16_d16_hi v38, v140 offset:0
	ds_write_b32 v3, v137 offset:2048
	ds_write_b16_d16_hi v38, v141 offset:1152
	ds_write_b32 v3, v138 offset:4096
	ds_write_b16_d16_hi v38, v142 offset:2304
	ds_write_b32 v3, v139 offset:6144
	ds_write_b16_d16_hi v38, v143 offset:3456
	s_waitcnt lgkmcnt(8)
	v_fma_f32 v136, v42, v154, v122
	v_fma_f32 v137, v42, v158, v122
	v_fma_f32 v138, v42, v162, v122
	v_fma_f32 v139, v42, v166, v122
	v_fmac_f32_e32 v136, v43, v155
	v_fmac_f32_e32 v137, v43, v159
	v_fmac_f32_e32 v138, v43, v163
	v_fmac_f32_e32 v139, v43, v167
	v_fmac_f32_e32 v136, v44, v156
	v_fmac_f32_e32 v137, v44, v160
	v_fmac_f32_e32 v138, v44, v164
	v_fmac_f32_e32 v139, v44, v168
	v_fmac_f32_e32 v136, v45, v157
	v_fmac_f32_e32 v137, v45, v161
	v_fmac_f32_e32 v138, v45, v165
	v_fmac_f32_e32 v139, v45, v169
	ds_read2st64_b32 v[154:155], v0 offset0:68 offset1:69
	ds_read2st64_b32 v[156:157], v0 offset0:70 offset1:71
	ds_read2st64_b32 v[158:159], v0 offset0:76 offset1:77
	ds_read2st64_b32 v[160:161], v0 offset0:78 offset1:79
	ds_read2st64_b32 v[162:163], v0 offset0:84 offset1:85
	ds_read2st64_b32 v[164:165], v0 offset0:86 offset1:87
	ds_read2st64_b32 v[166:167], v0 offset0:92 offset1:93
	ds_read2st64_b32 v[168:169], v0 offset0:94 offset1:95
	v_bfe_u32 v140, v136, 16, 1
	v_bfe_u32 v141, v137, 16, 1
	v_bfe_u32 v142, v138, 16, 1
	v_bfe_u32 v143, v139, 16, 1
	v_add3_u32 v140, v136, v140, s97
	v_add3_u32 v141, v137, v141, s97
	v_add3_u32 v142, v138, v142, s97
	v_add3_u32 v143, v139, v143, s97
	ds_write_b32 v3, v136 offset:8192
	ds_write_b16_d16_hi v38, v140 offset:4608
	ds_write_b32 v3, v137 offset:10240
	ds_write_b16_d16_hi v38, v141 offset:5760
	ds_write_b32 v3, v138 offset:12288
	ds_write_b16_d16_hi v38, v142 offset:6912
	ds_write_b32 v3, v139 offset:14336
	ds_write_b16_d16_hi v38, v143 offset:8064
	s_waitcnt lgkmcnt(8)
	v_fma_f32 v136, v123, v154, v127
	v_fma_f32 v137, v123, v158, v127
	v_fma_f32 v138, v123, v162, v127
	v_fma_f32 v139, v123, v166, v127
	v_fmac_f32_e32 v136, v124, v155
	v_fmac_f32_e32 v137, v124, v159
	v_fmac_f32_e32 v138, v124, v163
	v_fmac_f32_e32 v139, v124, v167
	v_fmac_f32_e32 v136, v125, v156
	v_fmac_f32_e32 v137, v125, v160
	v_fmac_f32_e32 v138, v125, v164
	v_fmac_f32_e32 v139, v125, v168
	v_fmac_f32_e32 v136, v126, v157
	v_fmac_f32_e32 v137, v126, v161
	v_fmac_f32_e32 v138, v126, v165
	v_fmac_f32_e32 v139, v126, v169
	ds_read2st64_b32 v[154:155], v0 offset0:100 offset1:101
	ds_read2st64_b32 v[156:157], v0 offset0:102 offset1:103
	ds_read2st64_b32 v[158:159], v0 offset0:108 offset1:109
	ds_read2st64_b32 v[160:161], v0 offset0:110 offset1:111
	ds_read2st64_b32 v[162:163], v0 offset0:116 offset1:117
	ds_read2st64_b32 v[164:165], v0 offset0:118 offset1:119
	ds_read2st64_b32 v[166:167], v0 offset0:124 offset1:125
	ds_read2st64_b32 v[168:169], v0 offset0:126 offset1:127
	v_bfe_u32 v140, v136, 16, 1
	v_bfe_u32 v141, v137, 16, 1
	v_bfe_u32 v142, v138, 16, 1
	v_bfe_u32 v143, v139, 16, 1
	v_add3_u32 v140, v136, v140, s97
	v_add3_u32 v141, v137, v141, s97
	v_add3_u32 v142, v138, v142, s97
	v_add3_u32 v143, v139, v143, s97
	ds_write_b32 v3, v136 offset:16384
	ds_write_b16_d16_hi v38, v140 offset:9216
	ds_write_b32 v3, v137 offset:18432
	ds_write_b16_d16_hi v38, v141 offset:10368
	ds_write_b32 v3, v138 offset:20480
	ds_write_b16_d16_hi v38, v142 offset:11520
	ds_write_b32 v3, v139 offset:22528
	ds_write_b16_d16_hi v38, v143 offset:12672
	s_waitcnt lgkmcnt(8)
	v_fma_f32 v136, v123, v154, v127
	v_fma_f32 v137, v123, v158, v127
	v_fma_f32 v138, v123, v162, v127
	v_fma_f32 v139, v123, v166, v127
	v_fmac_f32_e32 v136, v124, v155
	v_fmac_f32_e32 v137, v124, v159
	v_fmac_f32_e32 v138, v124, v163
	v_fmac_f32_e32 v139, v124, v167
	v_fmac_f32_e32 v136, v125, v156
	v_fmac_f32_e32 v137, v125, v160
	v_fmac_f32_e32 v138, v125, v164
	v_fmac_f32_e32 v139, v125, v168
	v_fmac_f32_e32 v136, v126, v157
	v_fmac_f32_e32 v137, v126, v161
	v_fmac_f32_e32 v138, v126, v165
	v_fmac_f32_e32 v139, v126, v169
	v_bfe_u32 v140, v136, 16, 1
	v_bfe_u32 v141, v137, 16, 1
	v_bfe_u32 v142, v138, 16, 1
	v_bfe_u32 v143, v139, 16, 1
	v_add3_u32 v140, v136, v140, s97
	v_add3_u32 v141, v137, v141, s97
	v_add3_u32 v142, v138, v142, s97
	v_add3_u32 v143, v139, v143, s97
	ds_write_b32 v3, v136 offset:24576
	ds_write_b16_d16_hi v38, v140 offset:13824
	ds_write_b32 v3, v137 offset:26624
	ds_write_b16_d16_hi v38, v141 offset:14976
	ds_write_b32 v3, v138 offset:28672
	ds_write_b16_d16_hi v38, v142 offset:16128
	ds_write_b32 v3, v139 offset:30720
	ds_write_b16_d16_hi v38, v143 offset:17280
	v_add3_u32 v37, s25, v37, v2
	v_and_b32_e32 v38, 15, v36
	v_and_b32_e32 v39, -16, v36
	v_lshlrev_b32_e32 v135, 2, v38
	v_mul_u32_u24_e32 v38, 0x90, v38
	v_add3_u32 v39, s65, v39, v38
	s_waitcnt lgkmcnt(0)
	s_barrier
	ds_read_b128 v[136:139], v39
	ds_read_b128 v[140:143], v39 offset:64
	s_waitcnt lgkmcnt(1)
	v_mfma_f32_16x16x32_bf16 v[136:139], v[136:139], v[20:23], 0
	v_lshrrev_b32_e32 v40, 2, v36
	v_and_b32_e32 v40, 0xfffffc, v40
	s_waitcnt lgkmcnt(0)
	v_mfma_f32_16x16x32_bf16 v[136:139], v[140:143], v[24:27], v[136:139]
	s_nop 7
	v_add_f32_e32 v38, v128, v136
	v_mul_f32_e32 v38, 0xbfb8aa3b, v38
	v_exp_f32_e32 v38, v38
	s_nop 0
	v_add_f32_e32 v38, 1.0, v38
	v_rcp_f32_e32 v136, v38
	v_add_lshl_u32 v38, v40, s60, 8
	v_add_f32_e32 v40, v128, v137
	v_mul_f32_e32 v40, 0xbfb8aa3b, v40
	v_exp_f32_e32 v40, v40
	v_add3_u32 v38, s13, v135, v38
	v_add_f32_e32 v135, v128, v139
	v_mul_f32_e32 v135, 0xbfb8aa3b, v135
	v_add_f32_e32 v40, 1.0, v40
	v_rcp_f32_e32 v40, v40
	v_exp_f32_e32 v135, v135
	ds_write2st64_b32 v38, v136, v40 offset1:1
	v_add_f32_e32 v40, v128, v138
	v_mul_f32_e32 v40, 0xbfb8aa3b, v40
	v_exp_f32_e32 v40, v40
	v_add_f32_e32 v135, 1.0, v135
	v_rcp_f32_e32 v135, v135
	v_add_f32_e32 v40, 1.0, v40
	v_rcp_f32_e32 v40, v40
	ds_write2st64_b32 v38, v40, v135 offset0:2 offset1:3
	ds_read_b128 v[136:139], v39 offset:2304
	ds_read_b128 v[140:143], v39 offset:2368
	s_waitcnt lgkmcnt(1)
	v_mfma_f32_16x16x32_bf16 v[136:139], v[136:139], v[20:23], 0
	s_waitcnt lgkmcnt(0)
	v_mfma_f32_16x16x32_bf16 v[136:139], v[140:143], v[24:27], v[136:139]
	s_nop 7
	v_add_f32_e32 v40, v128, v136
	v_add_f32_e32 v135, v128, v137
	v_mul_f32_e32 v40, 0xbfb8aa3b, v40
	v_mul_f32_e32 v135, 0xbfb8aa3b, v135
	v_exp_f32_e32 v40, v40
	v_exp_f32_e32 v135, v135
	v_add_f32_e32 v40, 1.0, v40
	v_add_f32_e32 v135, 1.0, v135
	v_rcp_f32_e32 v40, v40
	v_rcp_f32_e32 v135, v135
	ds_write2st64_b32 v38, v40, v135 offset0:16 offset1:17
	v_add_f32_e32 v40, v128, v138
	v_add_f32_e32 v135, v128, v139
	v_mul_f32_e32 v40, 0xbfb8aa3b, v40
	v_mul_f32_e32 v135, 0xbfb8aa3b, v135
	v_exp_f32_e32 v40, v40
	v_exp_f32_e32 v135, v135
	v_add_f32_e32 v40, 1.0, v40
	v_add_f32_e32 v135, 1.0, v135
	v_rcp_f32_e32 v40, v40
	v_rcp_f32_e32 v135, v135
	ds_write2st64_b32 v38, v40, v135 offset0:18 offset1:19
	ds_read_b128 v[136:139], v39 offset:4608
	ds_read_b128 v[140:143], v39 offset:4672
	s_waitcnt lgkmcnt(1)
	v_mfma_f32_16x16x32_bf16 v[136:139], v[136:139], v[20:23], 0
	s_waitcnt lgkmcnt(0)
	v_mfma_f32_16x16x32_bf16 v[136:139], v[140:143], v[24:27], v[136:139]
	s_nop 7
	v_add_f32_e32 v40, v128, v136
	v_add_f32_e32 v135, v128, v137
	v_mul_f32_e32 v40, 0xbfb8aa3b, v40
	v_mul_f32_e32 v135, 0xbfb8aa3b, v135
	v_exp_f32_e32 v40, v40
	v_exp_f32_e32 v135, v135
	v_add_f32_e32 v40, 1.0, v40
	v_add_f32_e32 v135, 1.0, v135
	v_rcp_f32_e32 v40, v40
	v_rcp_f32_e32 v135, v135
	ds_write2st64_b32 v38, v40, v135 offset0:32 offset1:33
	v_add_f32_e32 v40, v128, v138
	v_add_f32_e32 v135, v128, v139
	v_mul_f32_e32 v40, 0xbfb8aa3b, v40
	v_mul_f32_e32 v135, 0xbfb8aa3b, v135
	v_exp_f32_e32 v40, v40
	v_exp_f32_e32 v135, v135
	v_add_f32_e32 v40, 1.0, v40
	v_add_f32_e32 v135, 1.0, v135
	v_rcp_f32_e32 v40, v40
	v_rcp_f32_e32 v135, v135
	ds_write2st64_b32 v38, v40, v135 offset0:34 offset1:35
	ds_read_b128 v[136:139], v39 offset:6912
	ds_read_b128 v[140:143], v39 offset:6976
	s_waitcnt lgkmcnt(1)
	v_mfma_f32_16x16x32_bf16 v[136:139], v[136:139], v[20:23], 0
	s_waitcnt lgkmcnt(0)
	v_mfma_f32_16x16x32_bf16 v[136:139], v[140:143], v[24:27], v[136:139]
	s_nop 7
	v_add_f32_e32 v40, v128, v136
	v_add_f32_e32 v135, v128, v137
	v_mul_f32_e32 v40, 0xbfb8aa3b, v40
	v_mul_f32_e32 v135, 0xbfb8aa3b, v135
	v_exp_f32_e32 v40, v40
	v_exp_f32_e32 v135, v135
	v_add_f32_e32 v40, 1.0, v40
	v_add_f32_e32 v135, 1.0, v135
	v_rcp_f32_e32 v40, v40
	v_rcp_f32_e32 v135, v135
	ds_write2st64_b32 v38, v40, v135 offset0:48 offset1:49
	v_add_f32_e32 v40, v128, v138
	v_add_f32_e32 v135, v128, v139
	v_mul_f32_e32 v40, 0xbfb8aa3b, v40
	v_mul_f32_e32 v135, 0xbfb8aa3b, v135
	v_exp_f32_e32 v40, v40
	v_exp_f32_e32 v135, v135
	v_add_f32_e32 v40, 1.0, v40
	v_add_f32_e32 v135, 1.0, v135
	v_rcp_f32_e32 v40, v40
	v_rcp_f32_e32 v135, v135
	ds_write2st64_b32 v38, v40, v135 offset0:50 offset1:51
	ds_read_b128 v[136:139], v39 offset:9216
	ds_read_b128 v[140:143], v39 offset:9280
	s_waitcnt lgkmcnt(1)
	v_mfma_f32_16x16x32_bf16 v[136:139], v[136:139], v[28:31], 0
	s_waitcnt lgkmcnt(0)
	v_mfma_f32_16x16x32_bf16 v[136:139], v[140:143], v[32:35], v[136:139]
	s_waitcnt vmcnt(0)
	s_nop 6
	v_add_f32_e32 v40, v129, v136
	v_add_f32_e32 v135, v129, v137
	v_mul_f32_e32 v40, 0xbfb8aa3b, v40
	v_mul_f32_e32 v135, 0xbfb8aa3b, v135
	v_exp_f32_e32 v40, v40
	v_exp_f32_e32 v135, v135
	v_add_f32_e32 v40, 1.0, v40
	v_add_f32_e32 v135, 1.0, v135
	v_rcp_f32_e32 v40, v40
	v_rcp_f32_e32 v135, v135
	ds_write2st64_b32 v38, v40, v135 offset0:128 offset1:129
	v_add_f32_e32 v40, v129, v138
	v_add_f32_e32 v135, v129, v139
	v_mul_f32_e32 v40, 0xbfb8aa3b, v40
	v_mul_f32_e32 v135, 0xbfb8aa3b, v135
	v_exp_f32_e32 v40, v40
	v_exp_f32_e32 v135, v135
	v_add_f32_e32 v40, 1.0, v40
	v_add_f32_e32 v135, 1.0, v135
	v_rcp_f32_e32 v40, v40
	v_rcp_f32_e32 v135, v135
	ds_write2st64_b32 v38, v40, v135 offset0:130 offset1:131
	ds_read_b128 v[136:139], v39 offset:11520
	ds_read_b128 v[140:143], v39 offset:11584
	s_waitcnt lgkmcnt(1)
	v_mfma_f32_16x16x32_bf16 v[136:139], v[136:139], v[28:31], 0
	s_waitcnt lgkmcnt(0)
	v_mfma_f32_16x16x32_bf16 v[136:139], v[140:143], v[32:35], v[136:139]
	s_nop 7
	v_add_f32_e32 v40, v129, v136
	v_add_f32_e32 v135, v129, v137
	v_mul_f32_e32 v40, 0xbfb8aa3b, v40
	v_mul_f32_e32 v135, 0xbfb8aa3b, v135
	v_exp_f32_e32 v40, v40
	v_exp_f32_e32 v135, v135
	v_add_f32_e32 v40, 1.0, v40
	v_add_f32_e32 v135, 1.0, v135
	v_rcp_f32_e32 v40, v40
	v_rcp_f32_e32 v135, v135
	ds_write2st64_b32 v38, v40, v135 offset0:144 offset1:145
	v_add_f32_e32 v40, v129, v138
	v_add_f32_e32 v135, v129, v139
	v_mul_f32_e32 v40, 0xbfb8aa3b, v40
	v_mul_f32_e32 v135, 0xbfb8aa3b, v135
	v_exp_f32_e32 v40, v40
	v_exp_f32_e32 v135, v135
	v_add_f32_e32 v40, 1.0, v40
	v_add_f32_e32 v135, 1.0, v135
	v_rcp_f32_e32 v40, v40
	v_rcp_f32_e32 v135, v135
	ds_write2st64_b32 v38, v40, v135 offset0:146 offset1:147
	ds_read_b128 v[136:139], v39 offset:13824
	ds_read_b128 v[140:143], v39 offset:13888
	s_waitcnt lgkmcnt(1)
	v_mfma_f32_16x16x32_bf16 v[136:139], v[136:139], v[28:31], 0
	s_waitcnt lgkmcnt(0)
	v_mfma_f32_16x16x32_bf16 v[136:139], v[140:143], v[32:35], v[136:139]
	s_nop 7
	v_add_f32_e32 v40, v129, v136
	v_add_f32_e32 v135, v129, v137
	v_mul_f32_e32 v40, 0xbfb8aa3b, v40
	v_mul_f32_e32 v135, 0xbfb8aa3b, v135
	v_exp_f32_e32 v40, v40
	v_exp_f32_e32 v135, v135
	v_add_f32_e32 v40, 1.0, v40
	v_add_f32_e32 v135, 1.0, v135
	v_rcp_f32_e32 v40, v40
	v_rcp_f32_e32 v135, v135
	ds_write2st64_b32 v38, v40, v135 offset0:160 offset1:161
	v_add_f32_e32 v40, v129, v138
	v_add_f32_e32 v135, v129, v139
	v_mul_f32_e32 v40, 0xbfb8aa3b, v40
	v_mul_f32_e32 v135, 0xbfb8aa3b, v135
	v_exp_f32_e32 v40, v40
	v_exp_f32_e32 v135, v135
	v_add_f32_e32 v40, 1.0, v40
	v_add_f32_e32 v135, 1.0, v135
	v_rcp_f32_e32 v40, v40
	v_rcp_f32_e32 v135, v135
	ds_write2st64_b32 v38, v40, v135 offset0:162 offset1:163
	ds_read_b128 v[136:139], v39 offset:16128
	ds_read_b128 v[140:143], v39 offset:16192
	s_waitcnt lgkmcnt(1)
	v_mfma_f32_16x16x32_bf16 v[136:139], v[136:139], v[28:31], 0
	s_waitcnt lgkmcnt(0)
	v_mfma_f32_16x16x32_bf16 v[136:139], v[140:143], v[32:35], v[136:139]
	s_nop 7
	v_add_f32_e32 v39, v129, v136
	v_add_f32_e32 v40, v129, v137
	v_mul_f32_e32 v39, 0xbfb8aa3b, v39
	v_mul_f32_e32 v40, 0xbfb8aa3b, v40
	v_exp_f32_e32 v39, v39
	v_exp_f32_e32 v40, v40
	v_add_f32_e32 v39, 1.0, v39
	v_add_f32_e32 v40, 1.0, v40
	v_rcp_f32_e32 v39, v39
	v_rcp_f32_e32 v40, v40
	ds_write2st64_b32 v38, v39, v40 offset0:176 offset1:177
	v_add_f32_e32 v39, v129, v138
	v_add_f32_e32 v40, v129, v139
	v_mul_f32_e32 v39, 0xbfb8aa3b, v39
	v_mul_f32_e32 v40, 0xbfb8aa3b, v40
	v_exp_f32_e32 v39, v39
	v_exp_f32_e32 v40, v40
	v_add_f32_e32 v39, 1.0, v39
	v_add_f32_e32 v40, 1.0, v40
	v_rcp_f32_e32 v39, v39
	v_rcp_f32_e32 v40, v40
	ds_write2st64_b32 v38, v39, v40 offset0:178 offset1:179
	s_waitcnt lgkmcnt(0)
	s_barrier
	ds_read_b32 v38, v0
	ds_read_b32 v39, v0 offset:16384
	ds_read_b32 v40, v3
	s_waitcnt lgkmcnt(2)
	v_mul_f32_e32 v38, v130, v38
	v_mul_f32_e32 v38, 0x3fb8aa3b, v38
	v_exp_f32_e32 v38, v38
	s_waitcnt lgkmcnt(0)
	v_mul_f32_e32 v39, v39, v40
	v_fma_f32 v135, -v38, v38, 1.0
	v_max_f32_e32 v135, 0, v135
	v_sqrt_f32_e32 v135, v135
	s_nop 0
	v_mul_f32_e32 v39, v39, v135
	ds_write_b32 v0, v38
	ds_write_b32 v0, v39 offset:16384
	v_lshlrev_b32_e32 v38, 2, v134
	v_and_b32_e32 v40, 0xffffff00, v38
	v_add3_u32 v135, 0, v40, v2
	ds_read2st64_b32 v[38:39], v135 offset1:64
	v_add3_u32 v136, s24, v40, v2
	ds_read_b32 v136, v136
	v_add3_u32 v2, s25, v40, v2
	s_waitcnt lgkmcnt(1)
	v_mul_f32_e32 v38, v130, v38
	v_mul_f32_e32 v38, 0x3fb8aa3b, v38
	v_exp_f32_e32 v38, v38
	s_waitcnt lgkmcnt(0)
	v_mul_f32_e32 v39, v39, v136
	v_fma_f32 v137, -v38, v38, 1.0
	v_max_f32_e32 v137, 0, v137
	v_sqrt_f32_e32 v137, v137
	s_nop 0
	v_mul_f32_e32 v39, v39, v137
	ds_write2st64_b32 v135, v38, v39 offset1:64
	ds_read2st64_b32 v[38:39], v0 offset0:16 offset1:24
	ds_read2st64_b32 v[136:137], v0 offset0:80 offset1:88
	ds_read2st64_b32 v[138:139], v3 offset0:16 offset1:24
	s_waitcnt lgkmcnt(2)
	v_mul_f32_e32 v38, v130, v38
	v_mul_f32_e32 v39, v130, v39
	v_mul_f32_e32 v38, 0x3fb8aa3b, v38
	v_mul_f32_e32 v39, 0x3fb8aa3b, v39
	v_exp_f32_e32 v38, v38
	v_exp_f32_e32 v39, v39
	s_waitcnt lgkmcnt(0)
	v_mul_f32_e32 v136, v136, v138
	v_mul_f32_e32 v137, v137, v139
	v_fma_f32 v140, -v38, v38, 1.0
	v_fma_f32 v138, -v39, v39, 1.0
	v_max_f32_e32 v140, 0, v140
	v_max_f32_e32 v138, 0, v138
	v_sqrt_f32_e32 v140, v140
	v_sqrt_f32_e32 v138, v138
	v_mul_f32_e32 v136, v136, v140
	v_mul_f32_e32 v137, v137, v138
	ds_write2st64_b32 v0, v38, v39 offset0:16 offset1:24
	ds_write2st64_b32 v0, v136, v137 offset0:80 offset1:88
	ds_read2st64_b32 v[38:39], v0 offset0:32 offset1:40
	ds_read2st64_b32 v[136:137], v0 offset0:96 offset1:104
	ds_read2st64_b32 v[138:139], v3 offset0:32 offset1:40
	s_waitcnt lgkmcnt(2)
	v_mul_f32_e32 v38, v130, v38
	v_mul_f32_e32 v39, v130, v39
	v_mul_f32_e32 v38, 0x3fb8aa3b, v38
	v_mul_f32_e32 v39, 0x3fb8aa3b, v39
	v_exp_f32_e32 v38, v38
	v_exp_f32_e32 v39, v39
	s_waitcnt lgkmcnt(0)
	v_mul_f32_e32 v136, v136, v138
	v_mul_f32_e32 v137, v137, v139
	v_fma_f32 v140, -v38, v38, 1.0
	v_fma_f32 v138, -v39, v39, 1.0
	v_max_f32_e32 v140, 0, v140
	v_max_f32_e32 v138, 0, v138
	v_sqrt_f32_e32 v140, v140
	v_sqrt_f32_e32 v138, v138
	v_mul_f32_e32 v136, v136, v140
	v_mul_f32_e32 v137, v137, v138
	ds_write2st64_b32 v0, v38, v39 offset0:32 offset1:40
	ds_write2st64_b32 v0, v136, v137 offset0:96 offset1:104
	ds_read2st64_b32 v[38:39], v0 offset0:48 offset1:56
	ds_read2st64_b32 v[136:137], v0 offset0:112 offset1:120
	ds_read2st64_b32 v[138:139], v3 offset0:48 offset1:56
	s_waitcnt lgkmcnt(2)
	v_mul_f32_e32 v3, v130, v38
	v_mul_f32_e32 v3, 0x3fb8aa3b, v3
	v_exp_f32_e32 v3, v3
	v_mul_f32_e32 v39, v130, v39
	v_mul_f32_e32 v39, 0x3fb8aa3b, v39
	v_exp_f32_e32 v39, v39
	v_fma_f32 v38, -v3, v3, 1.0
	v_max_f32_e32 v38, 0, v38
	v_sqrt_f32_e32 v38, v38
	s_waitcnt lgkmcnt(0)
	v_mul_f32_e32 v136, v136, v138
	v_mul_f32_e32 v137, v137, v139
	v_mul_f32_e32 v38, v136, v38
	v_fma_f32 v136, -v39, v39, 1.0
	v_max_f32_e32 v136, 0, v136
	v_sqrt_f32_e32 v136, v136
	s_nop 0
	v_mul_f32_e32 v136, v137, v136
	ds_write2st64_b32 v0, v3, v39 offset0:48 offset1:56
	ds_write2st64_b32 v0, v38, v136 offset0:112 offset1:120
	ds_read_b32 v3, v0 offset:32768
	ds_read_b32 v38, v0 offset:49152
	ds_read_b32 v39, v37
	s_waitcnt lgkmcnt(2)
	v_mul_f32_e32 v3, v131, v3
	v_mul_f32_e32 v3, 0x3fb8aa3b, v3
	v_exp_f32_e32 v3, v3
	s_waitcnt lgkmcnt(0)
	v_mul_f32_e32 v38, v38, v39
	v_fma_f32 v136, -v3, v3, 1.0
	v_max_f32_e32 v136, 0, v136
	v_sqrt_f32_e32 v136, v136
	s_nop 0
	v_mul_f32_e32 v38, v38, v136
	ds_write_b32 v0, v3 offset:32768
	ds_write_b32 v0, v38 offset:49152
	ds_read2st64_b32 v[38:39], v135 offset0:128 offset1:192
	ds_read_b32 v2, v2
	s_waitcnt lgkmcnt(1)
	v_mul_f32_e32 v3, v131, v38
	v_mul_f32_e32 v3, 0x3fb8aa3b, v3
	v_exp_f32_e32 v3, v3
	s_waitcnt lgkmcnt(0)
	v_mul_f32_e32 v2, v39, v2
	v_fma_f32 v38, -v3, v3, 1.0
	v_max_f32_e32 v38, 0, v38
	v_sqrt_f32_e32 v38, v38
	s_nop 0
	v_mul_f32_e32 v2, v2, v38
	ds_write2st64_b32 v135, v3, v2 offset0:128 offset1:192
	ds_read2st64_b32 v[2:3], v0 offset0:144 offset1:152
	ds_read2st64_b32 v[38:39], v0 offset0:208 offset1:216
	ds_read2st64_b32 v[136:137], v37 offset0:16 offset1:24
	s_waitcnt lgkmcnt(2)
	v_mul_f32_e32 v2, v131, v2
	v_mul_f32_e32 v2, 0x3fb8aa3b, v2
	v_exp_f32_e32 v2, v2
	v_mul_f32_e32 v3, v131, v3
	v_mul_f32_e32 v3, 0x3fb8aa3b, v3
	v_exp_f32_e32 v3, v3
	v_fma_f32 v40, -v2, v2, 1.0
	v_max_f32_e32 v40, 0, v40
	v_sqrt_f32_e32 v40, v40
	s_waitcnt lgkmcnt(0)
	v_mul_f32_e32 v38, v38, v136
	v_mul_f32_e32 v39, v39, v137
	v_mul_f32_e32 v38, v38, v40
	v_fma_f32 v40, -v3, v3, 1.0
	v_max_f32_e32 v40, 0, v40
	v_sqrt_f32_e32 v40, v40
	s_nop 0
	v_mul_f32_e32 v39, v39, v40
	ds_write2st64_b32 v0, v2, v3 offset0:144 offset1:152
	ds_write2st64_b32 v0, v38, v39 offset0:208 offset1:216
	ds_read2st64_b32 v[2:3], v0 offset0:160 offset1:168
	ds_read2st64_b32 v[38:39], v0 offset0:224 offset1:232
	ds_read2st64_b32 v[136:137], v37 offset0:32 offset1:40
	s_waitcnt lgkmcnt(2)
	v_mul_f32_e32 v2, v131, v2
	v_mul_f32_e32 v2, 0x3fb8aa3b, v2
	v_exp_f32_e32 v2, v2
	v_mul_f32_e32 v3, v131, v3
	v_mul_f32_e32 v3, 0x3fb8aa3b, v3
	v_exp_f32_e32 v3, v3
	v_fma_f32 v40, -v2, v2, 1.0
	v_max_f32_e32 v40, 0, v40
	v_sqrt_f32_e32 v40, v40
	s_waitcnt lgkmcnt(0)
	v_mul_f32_e32 v38, v38, v136
	v_mul_f32_e32 v39, v39, v137
	v_mul_f32_e32 v38, v38, v40
	v_fma_f32 v40, -v3, v3, 1.0
	v_max_f32_e32 v40, 0, v40
	v_sqrt_f32_e32 v40, v40
	s_nop 0
	v_mul_f32_e32 v39, v39, v40
	ds_write2st64_b32 v0, v2, v3 offset0:160 offset1:168
	ds_write2st64_b32 v0, v38, v39 offset0:224 offset1:232
	ds_read2st64_b32 v[2:3], v0 offset0:176 offset1:184
	ds_read2st64_b32 v[38:39], v0 offset0:240 offset1:248
	ds_read2st64_b32 v[136:137], v37 offset0:48 offset1:56
	s_waitcnt lgkmcnt(2)
	v_mul_f32_e32 v2, v131, v2
	v_mul_f32_e32 v2, 0x3fb8aa3b, v2
	v_exp_f32_e32 v2, v2
	v_mul_f32_e32 v3, v131, v3
	v_mul_f32_e32 v3, 0x3fb8aa3b, v3
	v_exp_f32_e32 v3, v3
	v_fma_f32 v37, -v2, v2, 1.0
	v_max_f32_e32 v37, 0, v37
	v_sqrt_f32_e32 v37, v37
	s_waitcnt lgkmcnt(0)
	v_mul_f32_e32 v38, v38, v136
	v_mul_f32_e32 v39, v39, v137
	v_mul_f32_e32 v37, v38, v37
	v_fma_f32 v38, -v3, v3, 1.0
	v_max_f32_e32 v38, 0, v38
	v_sqrt_f32_e32 v38, v38
	s_nop 0
	v_mul_f32_e32 v38, v39, v38
	ds_write2st64_b32 v0, v2, v3 offset0:176 offset1:184
	ds_write2st64_b32 v0, v37, v38 offset0:240 offset1:248
	s_waitcnt lgkmcnt(0)
	s_barrier
	s_cbranch_vccnz .LBB0_286
	v_lshlrev_b32_e32 v2, 2, v36
	v_add_u32_e32 v0, s61, v2
	s_sub_u32 s35, s64, s61
	s_mov_b32 s25, 0
	s_mov_b32 s26, 56

.Lrc_chunk:
	s_cmp_gt_u32 s34, 3
	s_cbranch_scc1 .Lrc_stage
	ds_read_b128 v[134:137], v42 offset:768
	ds_read_b128 v[130:133], v42 offset:512
	ds_read_b64 v[142:143], v43 offset:0
	ds_read_b128 v[122:125], v42 offset:0
	ds_read_b128 v[126:129], v42 offset:256
	ds_read_b128 v[138:141], v42 offset:1024
	s_waitcnt lgkmcnt(0)
	ds_read_b128 v[166:169], v42 offset:2304
	ds_read_b128 v[162:165], v42 offset:2048
	ds_read_b64 v[174:175], v43 offset:1536
	ds_read_b128 v[154:157], v42 offset:1536
	ds_read_b128 v[158:161], v42 offset:1792
	ds_read_b128 v[170:173], v42 offset:2560
	v_pk_mul_f32 v[198:199], v[2:3], v[134:135] op_sel:[0,0] op_sel_hi:[1,0]
	v_pk_mul_f32 v[176:177], v[142:143], v[130:131] op_sel:[0,0] op_sel_hi:[1,0]
	v_pk_fma_f32 v[198:199], v[4:5], v[134:135], v[198:199] op_sel:[0,1,0] op_sel_hi:[1,1,1]
	v_pk_mul_f32 v[178:179], v[142:143], v[130:131] op_sel:[0,1] op_sel_hi:[1,1]
	v_pk_fma_f32 v[198:199], v[6:7], v[136:137], v[198:199] op_sel:[0,0,0] op_sel_hi:[1,0,1]
	v_pk_mul_f32 v[180:181], v[142:143], v[132:133] op_sel:[0,0] op_sel_hi:[1,0]
	v_pk_fma_f32 v[198:199], v[8:9], v[136:137], v[198:199] op_sel:[0,1,0] op_sel_hi:[1,1,1]
	v_pk_mul_f32 v[188:189], v[142:143], v[132:133] op_sel:[0,1] op_sel_hi:[1,1]
	v_pk_fma_f32 v[2:3], v[2:3], v[122:123], v[176:177] op_sel:[0,0,0] op_sel_hi:[1,0,1]
	v_add_f32_dpp v198, v198, v198 quad_perm:[1,0,3,2] row_mask:0xf bank_mask:0xf bound_ctrl:1
	v_add_f32_dpp v199, v199, v199 quad_perm:[1,0,3,2] row_mask:0xf bank_mask:0xf bound_ctrl:1
	v_pk_fma_f32 v[4:5], v[4:5], v[122:123], v[178:179] op_sel:[0,1,0] op_sel_hi:[1,1,1]
	v_add_f32_dpp v198, v198, v198 quad_perm:[2,3,0,1] row_mask:0xf bank_mask:0xf bound_ctrl:1
	v_add_f32_dpp v199, v199, v199 quad_perm:[2,3,0,1] row_mask:0xf bank_mask:0xf bound_ctrl:1
	v_pk_fma_f32 v[6:7], v[6:7], v[124:125], v[180:181] op_sel:[0,0,0] op_sel_hi:[1,0,1]
	v_add_f32_dpp v198, v198, v198 row_half_mirror row_mask:0xf bank_mask:0xf bound_ctrl:1
	v_add_f32_dpp v199, v199, v199 row_half_mirror row_mask:0xf bank_mask:0xf bound_ctrl:1
	v_pk_fma_f32 v[8:9], v[8:9], v[124:125], v[188:189] op_sel:[0,1,0] op_sel_hi:[1,1,1]
	v_add_f32_dpp v198, v198, v198 row_mirror row_mask:0xf bank_mask:0xf bound_ctrl:1
	v_add_f32_dpp v199, v199, v199 row_mirror row_mask:0xf bank_mask:0xf bound_ctrl:1
	v_pk_fma_f32 v[2:3], v[126:127], v[198:199], v[2:3] op_sel:[0,0,0] op_sel_hi:[0,1,1] neg_lo:[0,1,0] neg_hi:[0,1,0]
	v_pk_fma_f32 v[4:5], v[126:127], v[198:199], v[4:5] op_sel:[1,0,0] op_sel_hi:[1,1,1] neg_lo:[0,1,0] neg_hi:[0,1,0]
	v_pk_fma_f32 v[6:7], v[128:129], v[198:199], v[6:7] op_sel:[0,0,0] op_sel_hi:[0,1,1] neg_lo:[0,1,0] neg_hi:[0,1,0]
	v_pk_fma_f32 v[8:9], v[128:129], v[198:199], v[8:9] op_sel:[1,0,0] op_sel_hi:[1,1,1] neg_lo:[0,1,0] neg_hi:[0,1,0]
	v_pk_mul_f32 v[10:11], v[2:3], v[138:139] op_sel:[0,0] op_sel_hi:[1,0]
	v_pk_fma_f32 v[10:11], v[4:5], v[138:139], v[10:11] op_sel:[0,1,0] op_sel_hi:[1,1,1]
	v_pk_fma_f32 v[10:11], v[6:7], v[140:141], v[10:11] op_sel:[0,0,0] op_sel_hi:[1,0,1]
	v_pk_fma_f32 v[10:11], v[8:9], v[140:141], v[10:11] op_sel:[0,1,0] op_sel_hi:[1,1,1]
	s_waitcnt lgkmcnt(0)
	ds_read_b128 v[134:137], v42 offset:3840
	ds_read_b128 v[130:133], v42 offset:3584
	ds_read_b64 v[142:143], v43 offset:3072
	ds_read_b128 v[122:125], v42 offset:3072
	ds_read_b128 v[126:129], v42 offset:3328
	ds_read_b128 v[138:141], v42 offset:4096
	v_pk_mul_f32 v[198:199], v[2:3], v[166:167] op_sel:[0,0] op_sel_hi:[1,0]
	v_pk_mul_f32 v[176:177], v[174:175], v[162:163] op_sel:[0,0] op_sel_hi:[1,0]
	v_pk_fma_f32 v[198:199], v[4:5], v[166:167], v[198:199] op_sel:[0,1,0] op_sel_hi:[1,1,1]
	v_pk_mul_f32 v[178:179], v[174:175], v[162:163] op_sel:[0,1] op_sel_hi:[1,1]
	v_pk_fma_f32 v[198:199], v[6:7], v[168:169], v[198:199] op_sel:[0,0,0] op_sel_hi:[1,0,1]
	v_pk_mul_f32 v[180:181], v[174:175], v[164:165] op_sel:[0,0] op_sel_hi:[1,0]
	v_pk_fma_f32 v[198:199], v[8:9], v[168:169], v[198:199] op_sel:[0,1,0] op_sel_hi:[1,1,1]
	v_pk_mul_f32 v[188:189], v[174:175], v[164:165] op_sel:[0,1] op_sel_hi:[1,1]
	v_pk_fma_f32 v[2:3], v[2:3], v[154:155], v[176:177] op_sel:[0,0,0] op_sel_hi:[1,0,1]
	v_add_f32_dpp v198, v198, v198 quad_perm:[1,0,3,2] row_mask:0xf bank_mask:0xf bound_ctrl:1
	v_add_f32_dpp v199, v199, v199 quad_perm:[1,0,3,2] row_mask:0xf bank_mask:0xf bound_ctrl:1
	v_pk_fma_f32 v[4:5], v[4:5], v[154:155], v[178:179] op_sel:[0,1,0] op_sel_hi:[1,1,1]
	v_add_f32_dpp v198, v198, v198 quad_perm:[2,3,0,1] row_mask:0xf bank_mask:0xf bound_ctrl:1
	v_add_f32_dpp v199, v199, v199 quad_perm:[2,3,0,1] row_mask:0xf bank_mask:0xf bound_ctrl:1
	v_pk_fma_f32 v[6:7], v[6:7], v[156:157], v[180:181] op_sel:[0,0,0] op_sel_hi:[1,0,1]
	v_add_f32_dpp v198, v198, v198 row_half_mirror row_mask:0xf bank_mask:0xf bound_ctrl:1
	v_add_f32_dpp v199, v199, v199 row_half_mirror row_mask:0xf bank_mask:0xf bound_ctrl:1
	v_pk_fma_f32 v[8:9], v[8:9], v[156:157], v[188:189] op_sel:[0,1,0] op_sel_hi:[1,1,1]
	v_add_f32_dpp v198, v198, v198 row_mirror row_mask:0xf bank_mask:0xf bound_ctrl:1
	v_add_f32_dpp v199, v199, v199 row_mirror row_mask:0xf bank_mask:0xf bound_ctrl:1
	v_pk_fma_f32 v[2:3], v[158:159], v[198:199], v[2:3] op_sel:[0,0,0] op_sel_hi:[0,1,1] neg_lo:[0,1,0] neg_hi:[0,1,0]
	v_pk_fma_f32 v[4:5], v[158:159], v[198:199], v[4:5] op_sel:[1,0,0] op_sel_hi:[1,1,1] neg_lo:[0,1,0] neg_hi:[0,1,0]
	v_pk_fma_f32 v[6:7], v[160:161], v[198:199], v[6:7] op_sel:[0,0,0] op_sel_hi:[0,1,1] neg_lo:[0,1,0] neg_hi:[0,1,0]
	v_pk_fma_f32 v[8:9], v[160:161], v[198:199], v[8:9] op_sel:[1,0,0] op_sel_hi:[1,1,1] neg_lo:[0,1,0] neg_hi:[0,1,0]
	v_pk_mul_f32 v[12:13], v[2:3], v[170:171] op_sel:[0,0] op_sel_hi:[1,0]
	v_pk_fma_f32 v[12:13], v[4:5], v[170:171], v[12:13] op_sel:[0,1,0] op_sel_hi:[1,1,1]
	v_pk_fma_f32 v[12:13], v[6:7], v[172:173], v[12:13] op_sel:[0,0,0] op_sel_hi:[1,0,1]
	v_pk_fma_f32 v[12:13], v[8:9], v[172:173], v[12:13] op_sel:[0,1,0] op_sel_hi:[1,1,1]
	s_waitcnt lgkmcnt(0)
	ds_read_b128 v[166:169], v42 offset:5376
	ds_read_b128 v[162:165], v42 offset:5120
	ds_read_b64 v[174:175], v43 offset:4608
	ds_read_b128 v[154:157], v42 offset:4608
	ds_read_b128 v[158:161], v42 offset:4864
	ds_read_b128 v[170:173], v42 offset:5632
	v_pk_mul_f32 v[198:199], v[2:3], v[134:135] op_sel:[0,0] op_sel_hi:[1,0]
	v_pk_mul_f32 v[176:177], v[142:143], v[130:131] op_sel:[0,0] op_sel_hi:[1,0]
	v_pk_fma_f32 v[198:199], v[4:5], v[134:135], v[198:199] op_sel:[0,1,0] op_sel_hi:[1,1,1]
	v_pk_mul_f32 v[178:179], v[142:143], v[130:131] op_sel:[0,1] op_sel_hi:[1,1]
	v_pk_fma_f32 v[198:199], v[6:7], v[136:137], v[198:199] op_sel:[0,0,0] op_sel_hi:[1,0,1]
	v_pk_mul_f32 v[180:181], v[142:143], v[132:133] op_sel:[0,0] op_sel_hi:[1,0]
	v_pk_fma_f32 v[198:199], v[8:9], v[136:137], v[198:199] op_sel:[0,1,0] op_sel_hi:[1,1,1]
	v_pk_mul_f32 v[188:189], v[142:143], v[132:133] op_sel:[0,1] op_sel_hi:[1,1]
	v_pk_fma_f32 v[2:3], v[2:3], v[122:123], v[176:177] op_sel:[0,0,0] op_sel_hi:[1,0,1]
	v_add_f32_dpp v198, v198, v198 quad_perm:[1,0,3,2] row_mask:0xf bank_mask:0xf bound_ctrl:1
	v_add_f32_dpp v199, v199, v199 quad_perm:[1,0,3,2] row_mask:0xf bank_mask:0xf bound_ctrl:1
	v_pk_fma_f32 v[4:5], v[4:5], v[122:123], v[178:179] op_sel:[0,1,0] op_sel_hi:[1,1,1]
	v_add_f32_dpp v198, v198, v198 quad_perm:[2,3,0,1] row_mask:0xf bank_mask:0xf bound_ctrl:1
	v_add_f32_dpp v199, v199, v199 quad_perm:[2,3,0,1] row_mask:0xf bank_mask:0xf bound_ctrl:1
	v_pk_fma_f32 v[6:7], v[6:7], v[124:125], v[180:181] op_sel:[0,0,0] op_sel_hi:[1,0,1]
	v_add_f32_dpp v198, v198, v198 row_half_mirror row_mask:0xf bank_mask:0xf bound_ctrl:1
	v_add_f32_dpp v199, v199, v199 row_half_mirror row_mask:0xf bank_mask:0xf bound_ctrl:1
	v_pk_fma_f32 v[8:9], v[8:9], v[124:125], v[188:189] op_sel:[0,1,0] op_sel_hi:[1,1,1]
	v_add_f32_dpp v198, v198, v198 row_mirror row_mask:0xf bank_mask:0xf bound_ctrl:1
	v_add_f32_dpp v199, v199, v199 row_mirror row_mask:0xf bank_mask:0xf bound_ctrl:1
	v_pk_fma_f32 v[2:3], v[126:127], v[198:199], v[2:3] op_sel:[0,0,0] op_sel_hi:[0,1,1] neg_lo:[0,1,0] neg_hi:[0,1,0]
	v_pk_fma_f32 v[4:5], v[126:127], v[198:199], v[4:5] op_sel:[1,0,0] op_sel_hi:[1,1,1] neg_lo:[0,1,0] neg_hi:[0,1,0]
	v_pk_fma_f32 v[6:7], v[128:129], v[198:199], v[6:7] op_sel:[0,0,0] op_sel_hi:[0,1,1] neg_lo:[0,1,0] neg_hi:[0,1,0]
	v_pk_fma_f32 v[8:9], v[128:129], v[198:199], v[8:9] op_sel:[1,0,0] op_sel_hi:[1,1,1] neg_lo:[0,1,0] neg_hi:[0,1,0]
	v_pk_mul_f32 v[14:15], v[2:3], v[138:139] op_sel:[0,0] op_sel_hi:[1,0]
	v_pk_fma_f32 v[14:15], v[4:5], v[138:139], v[14:15] op_sel:[0,1,0] op_sel_hi:[1,1,1]
	v_pk_fma_f32 v[14:15], v[6:7], v[140:141], v[14:15] op_sel:[0,0,0] op_sel_hi:[1,0,1]
	v_pk_fma_f32 v[14:15], v[8:9], v[140:141], v[14:15] op_sel:[0,1,0] op_sel_hi:[1,1,1]
	s_waitcnt lgkmcnt(0)
	ds_read_b128 v[134:137], v42 offset:6912
	ds_read_b128 v[130:133], v42 offset:6656
	ds_read_b64 v[142:143], v43 offset:6144
	ds_read_b128 v[122:125], v42 offset:6144
	ds_read_b128 v[126:129], v42 offset:6400
	ds_read_b128 v[138:141], v42 offset:7168
	v_pk_mul_f32 v[198:199], v[2:3], v[166:167] op_sel:[0,0] op_sel_hi:[1,0]
	v_pk_mul_f32 v[176:177], v[174:175], v[162:163] op_sel:[0,0] op_sel_hi:[1,0]
	v_pk_fma_f32 v[198:199], v[4:5], v[166:167], v[198:199] op_sel:[0,1,0] op_sel_hi:[1,1,1]
	v_pk_mul_f32 v[178:179], v[174:175], v[162:163] op_sel:[0,1] op_sel_hi:[1,1]
	v_pk_fma_f32 v[198:199], v[6:7], v[168:169], v[198:199] op_sel:[0,0,0] op_sel_hi:[1,0,1]
	v_pk_mul_f32 v[180:181], v[174:175], v[164:165] op_sel:[0,0] op_sel_hi:[1,0]
	v_pk_fma_f32 v[198:199], v[8:9], v[168:169], v[198:199] op_sel:[0,1,0] op_sel_hi:[1,1,1]
	v_pk_mul_f32 v[188:189], v[174:175], v[164:165] op_sel:[0,1] op_sel_hi:[1,1]
	v_pk_fma_f32 v[2:3], v[2:3], v[154:155], v[176:177] op_sel:[0,0,0] op_sel_hi:[1,0,1]
	v_add_f32_dpp v198, v198, v198 quad_perm:[1,0,3,2] row_mask:0xf bank_mask:0xf bound_ctrl:1
	v_add_f32_dpp v199, v199, v199 quad_perm:[1,0,3,2] row_mask:0xf bank_mask:0xf bound_ctrl:1
	v_pk_fma_f32 v[4:5], v[4:5], v[154:155], v[178:179] op_sel:[0,1,0] op_sel_hi:[1,1,1]
	v_add_f32_dpp v198, v198, v198 quad_perm:[2,3,0,1] row_mask:0xf bank_mask:0xf bound_ctrl:1
	v_add_f32_dpp v199, v199, v199 quad_perm:[2,3,0,1] row_mask:0xf bank_mask:0xf bound_ctrl:1
	v_pk_fma_f32 v[6:7], v[6:7], v[156:157], v[180:181] op_sel:[0,0,0] op_sel_hi:[1,0,1]
	v_add_f32_dpp v198, v198, v198 row_half_mirror row_mask:0xf bank_mask:0xf bound_ctrl:1
	v_add_f32_dpp v199, v199, v199 row_half_mirror row_mask:0xf bank_mask:0xf bound_ctrl:1
	v_pk_fma_f32 v[8:9], v[8:9], v[156:157], v[188:189] op_sel:[0,1,0] op_sel_hi:[1,1,1]
	v_add_f32_dpp v198, v198, v198 row_mirror row_mask:0xf bank_mask:0xf bound_ctrl:1
	v_add_f32_dpp v199, v199, v199 row_mirror row_mask:0xf bank_mask:0xf bound_ctrl:1
	v_pk_fma_f32 v[2:3], v[158:159], v[198:199], v[2:3] op_sel:[0,0,0] op_sel_hi:[0,1,1] neg_lo:[0,1,0] neg_hi:[0,1,0]
	v_pk_fma_f32 v[4:5], v[158:159], v[198:199], v[4:5] op_sel:[1,0,0] op_sel_hi:[1,1,1] neg_lo:[0,1,0] neg_hi:[0,1,0]
	v_pk_fma_f32 v[6:7], v[160:161], v[198:199], v[6:7] op_sel:[0,0,0] op_sel_hi:[0,1,1] neg_lo:[0,1,0] neg_hi:[0,1,0]
	v_pk_fma_f32 v[8:9], v[160:161], v[198:199], v[8:9] op_sel:[1,0,0] op_sel_hi:[1,1,1] neg_lo:[0,1,0] neg_hi:[0,1,0]
	v_pk_mul_f32 v[16:17], v[2:3], v[170:171] op_sel:[0,0] op_sel_hi:[1,0]
	v_pk_fma_f32 v[16:17], v[4:5], v[170:171], v[16:17] op_sel:[0,1,0] op_sel_hi:[1,1,1]
	v_pk_fma_f32 v[16:17], v[6:7], v[172:173], v[16:17] op_sel:[0,0,0] op_sel_hi:[1,0,1]
	v_pk_fma_f32 v[16:17], v[8:9], v[172:173], v[16:17] op_sel:[0,1,0] op_sel_hi:[1,1,1]
	s_waitcnt lgkmcnt(0)
	ds_read_b128 v[166:169], v42 offset:8448
	ds_read_b128 v[162:165], v42 offset:8192
	ds_read_b64 v[174:175], v43 offset:7680
	ds_read_b128 v[154:157], v42 offset:7680
	ds_read_b128 v[158:161], v42 offset:7936
	ds_read_b128 v[170:173], v42 offset:8704
	v_pk_mul_f32 v[198:199], v[2:3], v[134:135] op_sel:[0,0] op_sel_hi:[1,0]
	v_pk_mul_f32 v[176:177], v[142:143], v[130:131] op_sel:[0,0] op_sel_hi:[1,0]
	v_pk_fma_f32 v[198:199], v[4:5], v[134:135], v[198:199] op_sel:[0,1,0] op_sel_hi:[1,1,1]
	v_pk_mul_f32 v[178:179], v[142:143], v[130:131] op_sel:[0,1] op_sel_hi:[1,1]
	v_pk_fma_f32 v[198:199], v[6:7], v[136:137], v[198:199] op_sel:[0,0,0] op_sel_hi:[1,0,1]
	v_pk_mul_f32 v[180:181], v[142:143], v[132:133] op_sel:[0,0] op_sel_hi:[1,0]
	v_pk_fma_f32 v[198:199], v[8:9], v[136:137], v[198:199] op_sel:[0,1,0] op_sel_hi:[1,1,1]
	v_pk_mul_f32 v[188:189], v[142:143], v[132:133] op_sel:[0,1] op_sel_hi:[1,1]
	v_pk_fma_f32 v[2:3], v[2:3], v[122:123], v[176:177] op_sel:[0,0,0] op_sel_hi:[1,0,1]
	v_add_f32_dpp v198, v198, v198 quad_perm:[1,0,3,2] row_mask:0xf bank_mask:0xf bound_ctrl:1
	v_add_f32_dpp v199, v199, v199 quad_perm:[1,0,3,2] row_mask:0xf bank_mask:0xf bound_ctrl:1
	v_pk_fma_f32 v[4:5], v[4:5], v[122:123], v[178:179] op_sel:[0,1,0] op_sel_hi:[1,1,1]
	v_add_f32_dpp v198, v198, v198 quad_perm:[2,3,0,1] row_mask:0xf bank_mask:0xf bound_ctrl:1
	v_add_f32_dpp v199, v199, v199 quad_perm:[2,3,0,1] row_mask:0xf bank_mask:0xf bound_ctrl:1
	v_pk_fma_f32 v[6:7], v[6:7], v[124:125], v[180:181] op_sel:[0,0,0] op_sel_hi:[1,0,1]
	v_add_f32_dpp v198, v198, v198 row_half_mirror row_mask:0xf bank_mask:0xf bound_ctrl:1
	v_add_f32_dpp v199, v199, v199 row_half_mirror row_mask:0xf bank_mask:0xf bound_ctrl:1
	v_pk_fma_f32 v[8:9], v[8:9], v[124:125], v[188:189] op_sel:[0,1,0] op_sel_hi:[1,1,1]
	v_add_f32_dpp v198, v198, v198 row_mirror row_mask:0xf bank_mask:0xf bound_ctrl:1
	v_add_f32_dpp v199, v199, v199 row_mirror row_mask:0xf bank_mask:0xf bound_ctrl:1
	v_pk_fma_f32 v[2:3], v[126:127], v[198:199], v[2:3] op_sel:[0,0,0] op_sel_hi:[0,1,1] neg_lo:[0,1,0] neg_hi:[0,1,0]
	v_pk_fma_f32 v[4:5], v[126:127], v[198:199], v[4:5] op_sel:[1,0,0] op_sel_hi:[1,1,1] neg_lo:[0,1,0] neg_hi:[0,1,0]
	v_pk_fma_f32 v[6:7], v[128:129], v[198:199], v[6:7] op_sel:[0,0,0] op_sel_hi:[0,1,1] neg_lo:[0,1,0] neg_hi:[0,1,0]
	v_pk_fma_f32 v[8:9], v[128:129], v[198:199], v[8:9] op_sel:[1,0,0] op_sel_hi:[1,1,1] neg_lo:[0,1,0] neg_hi:[0,1,0]
	v_pk_mul_f32 v[18:19], v[2:3], v[138:139] op_sel:[0,0] op_sel_hi:[1,0]
	v_pk_fma_f32 v[18:19], v[4:5], v[138:139], v[18:19] op_sel:[0,1,0] op_sel_hi:[1,1,1]
	v_pk_fma_f32 v[18:19], v[6:7], v[140:141], v[18:19] op_sel:[0,0,0] op_sel_hi:[1,0,1]
	v_pk_fma_f32 v[18:19], v[8:9], v[140:141], v[18:19] op_sel:[0,1,0] op_sel_hi:[1,1,1]
	s_waitcnt lgkmcnt(0)
	ds_read_b128 v[134:137], v42 offset:9984
	ds_read_b128 v[130:133], v42 offset:9728
	ds_read_b64 v[142:143], v43 offset:9216
	ds_read_b128 v[122:125], v42 offset:9216
	ds_read_b128 v[126:129], v42 offset:9472
	ds_read_b128 v[138:141], v42 offset:10240
	v_pk_mul_f32 v[198:199], v[2:3], v[166:167] op_sel:[0,0] op_sel_hi:[1,0]
	v_pk_mul_f32 v[176:177], v[174:175], v[162:163] op_sel:[0,0] op_sel_hi:[1,0]
	v_pk_fma_f32 v[198:199], v[4:5], v[166:167], v[198:199] op_sel:[0,1,0] op_sel_hi:[1,1,1]
	v_pk_mul_f32 v[178:179], v[174:175], v[162:163] op_sel:[0,1] op_sel_hi:[1,1]
	v_pk_fma_f32 v[198:199], v[6:7], v[168:169], v[198:199] op_sel:[0,0,0] op_sel_hi:[1,0,1]
	v_pk_mul_f32 v[180:181], v[174:175], v[164:165] op_sel:[0,0] op_sel_hi:[1,0]
	v_pk_fma_f32 v[198:199], v[8:9], v[168:169], v[198:199] op_sel:[0,1,0] op_sel_hi:[1,1,1]
	v_pk_mul_f32 v[188:189], v[174:175], v[164:165] op_sel:[0,1] op_sel_hi:[1,1]
	v_pk_fma_f32 v[2:3], v[2:3], v[154:155], v[176:177] op_sel:[0,0,0] op_sel_hi:[1,0,1]
	v_add_f32_dpp v198, v198, v198 quad_perm:[1,0,3,2] row_mask:0xf bank_mask:0xf bound_ctrl:1
	v_add_f32_dpp v199, v199, v199 quad_perm:[1,0,3,2] row_mask:0xf bank_mask:0xf bound_ctrl:1
	v_pk_fma_f32 v[4:5], v[4:5], v[154:155], v[178:179] op_sel:[0,1,0] op_sel_hi:[1,1,1]
	v_add_f32_dpp v198, v198, v198 quad_perm:[2,3,0,1] row_mask:0xf bank_mask:0xf bound_ctrl:1
	v_add_f32_dpp v199, v199, v199 quad_perm:[2,3,0,1] row_mask:0xf bank_mask:0xf bound_ctrl:1
	v_pk_fma_f32 v[6:7], v[6:7], v[156:157], v[180:181] op_sel:[0,0,0] op_sel_hi:[1,0,1]
	v_add_f32_dpp v198, v198, v198 row_half_mirror row_mask:0xf bank_mask:0xf bound_ctrl:1
	v_add_f32_dpp v199, v199, v199 row_half_mirror row_mask:0xf bank_mask:0xf bound_ctrl:1
	v_pk_fma_f32 v[8:9], v[8:9], v[156:157], v[188:189] op_sel:[0,1,0] op_sel_hi:[1,1,1]
	v_add_f32_dpp v198, v198, v198 row_mirror row_mask:0xf bank_mask:0xf bound_ctrl:1
	v_add_f32_dpp v199, v199, v199 row_mirror row_mask:0xf bank_mask:0xf bound_ctrl:1
	v_pk_fma_f32 v[2:3], v[158:159], v[198:199], v[2:3] op_sel:[0,0,0] op_sel_hi:[0,1,1] neg_lo:[0,1,0] neg_hi:[0,1,0]
	v_pk_fma_f32 v[4:5], v[158:159], v[198:199], v[4:5] op_sel:[1,0,0] op_sel_hi:[1,1,1] neg_lo:[0,1,0] neg_hi:[0,1,0]
	v_pk_fma_f32 v[6:7], v[160:161], v[198:199], v[6:7] op_sel:[0,0,0] op_sel_hi:[0,1,1] neg_lo:[0,1,0] neg_hi:[0,1,0]
	v_pk_fma_f32 v[8:9], v[160:161], v[198:199], v[8:9] op_sel:[1,0,0] op_sel_hi:[1,1,1] neg_lo:[0,1,0] neg_hi:[0,1,0]
	v_pk_mul_f32 v[20:21], v[2:3], v[170:171] op_sel:[0,0] op_sel_hi:[1,0]
	v_pk_fma_f32 v[20:21], v[4:5], v[170:171], v[20:21] op_sel:[0,1,0] op_sel_hi:[1,1,1]
	v_pk_fma_f32 v[20:21], v[6:7], v[172:173], v[20:21] op_sel:[0,0,0] op_sel_hi:[1,0,1]
	v_pk_fma_f32 v[20:21], v[8:9], v[172:173], v[20:21] op_sel:[0,1,0] op_sel_hi:[1,1,1]
	s_waitcnt lgkmcnt(0)
	ds_read_b128 v[166:169], v42 offset:11520
	ds_read_b128 v[162:165], v42 offset:11264
	ds_read_b64 v[174:175], v43 offset:10752
	ds_read_b128 v[154:157], v42 offset:10752
	ds_read_b128 v[158:161], v42 offset:11008
	ds_read_b128 v[170:173], v42 offset:11776
	v_pk_mul_f32 v[198:199], v[2:3], v[134:135] op_sel:[0,0] op_sel_hi:[1,0]
	v_pk_mul_f32 v[176:177], v[142:143], v[130:131] op_sel:[0,0] op_sel_hi:[1,0]
	v_pk_fma_f32 v[198:199], v[4:5], v[134:135], v[198:199] op_sel:[0,1,0] op_sel_hi:[1,1,1]
	v_pk_mul_f32 v[178:179], v[142:143], v[130:131] op_sel:[0,1] op_sel_hi:[1,1]
	v_pk_fma_f32 v[198:199], v[6:7], v[136:137], v[198:199] op_sel:[0,0,0] op_sel_hi:[1,0,1]
	v_pk_mul_f32 v[180:181], v[142:143], v[132:133] op_sel:[0,0] op_sel_hi:[1,0]
	v_pk_fma_f32 v[198:199], v[8:9], v[136:137], v[198:199] op_sel:[0,1,0] op_sel_hi:[1,1,1]
	v_pk_mul_f32 v[188:189], v[142:143], v[132:133] op_sel:[0,1] op_sel_hi:[1,1]
	v_pk_fma_f32 v[2:3], v[2:3], v[122:123], v[176:177] op_sel:[0,0,0] op_sel_hi:[1,0,1]
	v_add_f32_dpp v198, v198, v198 quad_perm:[1,0,3,2] row_mask:0xf bank_mask:0xf bound_ctrl:1
	v_add_f32_dpp v199, v199, v199 quad_perm:[1,0,3,2] row_mask:0xf bank_mask:0xf bound_ctrl:1
	v_pk_fma_f32 v[4:5], v[4:5], v[122:123], v[178:179] op_sel:[0,1,0] op_sel_hi:[1,1,1]
	v_add_f32_dpp v198, v198, v198 quad_perm:[2,3,0,1] row_mask:0xf bank_mask:0xf bound_ctrl:1
	v_add_f32_dpp v199, v199, v199 quad_perm:[2,3,0,1] row_mask:0xf bank_mask:0xf bound_ctrl:1
	v_pk_fma_f32 v[6:7], v[6:7], v[124:125], v[180:181] op_sel:[0,0,0] op_sel_hi:[1,0,1]
	v_add_f32_dpp v198, v198, v198 row_half_mirror row_mask:0xf bank_mask:0xf bound_ctrl:1
	v_add_f32_dpp v199, v199, v199 row_half_mirror row_mask:0xf bank_mask:0xf bound_ctrl:1
	v_pk_fma_f32 v[8:9], v[8:9], v[124:125], v[188:189] op_sel:[0,1,0] op_sel_hi:[1,1,1]
	v_add_f32_dpp v198, v198, v198 row_mirror row_mask:0xf bank_mask:0xf bound_ctrl:1
	v_add_f32_dpp v199, v199, v199 row_mirror row_mask:0xf bank_mask:0xf bound_ctrl:1
	v_pk_fma_f32 v[2:3], v[126:127], v[198:199], v[2:3] op_sel:[0,0,0] op_sel_hi:[0,1,1] neg_lo:[0,1,0] neg_hi:[0,1,0]
	v_pk_fma_f32 v[4:5], v[126:127], v[198:199], v[4:5] op_sel:[1,0,0] op_sel_hi:[1,1,1] neg_lo:[0,1,0] neg_hi:[0,1,0]
	v_pk_fma_f32 v[6:7], v[128:129], v[198:199], v[6:7] op_sel:[0,0,0] op_sel_hi:[0,1,1] neg_lo:[0,1,0] neg_hi:[0,1,0]
	v_pk_fma_f32 v[8:9], v[128:129], v[198:199], v[8:9] op_sel:[1,0,0] op_sel_hi:[1,1,1] neg_lo:[0,1,0] neg_hi:[0,1,0]
	v_pk_mul_f32 v[22:23], v[2:3], v[138:139] op_sel:[0,0] op_sel_hi:[1,0]
	v_pk_fma_f32 v[22:23], v[4:5], v[138:139], v[22:23] op_sel:[0,1,0] op_sel_hi:[1,1,1]
	v_pk_fma_f32 v[22:23], v[6:7], v[140:141], v[22:23] op_sel:[0,0,0] op_sel_hi:[1,0,1]
	v_pk_fma_f32 v[22:23], v[8:9], v[140:141], v[22:23] op_sel:[0,1,0] op_sel_hi:[1,1,1]
	s_waitcnt lgkmcnt(0)
	ds_read_b128 v[134:137], v42 offset:13056
	ds_read_b128 v[130:133], v42 offset:12800
	ds_read_b64 v[142:143], v43 offset:12288
	ds_read_b128 v[122:125], v42 offset:12288
	ds_read_b128 v[126:129], v42 offset:12544
	ds_read_b128 v[138:141], v42 offset:13312
	v_pk_mul_f32 v[198:199], v[2:3], v[166:167] op_sel:[0,0] op_sel_hi:[1,0]
	v_pk_mul_f32 v[176:177], v[174:175], v[162:163] op_sel:[0,0] op_sel_hi:[1,0]
	v_pk_fma_f32 v[198:199], v[4:5], v[166:167], v[198:199] op_sel:[0,1,0] op_sel_hi:[1,1,1]
	v_pk_mul_f32 v[178:179], v[174:175], v[162:163] op_sel:[0,1] op_sel_hi:[1,1]
	v_pk_fma_f32 v[198:199], v[6:7], v[168:169], v[198:199] op_sel:[0,0,0] op_sel_hi:[1,0,1]
	v_pk_mul_f32 v[180:181], v[174:175], v[164:165] op_sel:[0,0] op_sel_hi:[1,0]
	v_pk_fma_f32 v[198:199], v[8:9], v[168:169], v[198:199] op_sel:[0,1,0] op_sel_hi:[1,1,1]
	v_pk_mul_f32 v[188:189], v[174:175], v[164:165] op_sel:[0,1] op_sel_hi:[1,1]
	v_pk_fma_f32 v[2:3], v[2:3], v[154:155], v[176:177] op_sel:[0,0,0] op_sel_hi:[1,0,1]
	v_add_f32_dpp v198, v198, v198 quad_perm:[1,0,3,2] row_mask:0xf bank_mask:0xf bound_ctrl:1
	v_add_f32_dpp v199, v199, v199 quad_perm:[1,0,3,2] row_mask:0xf bank_mask:0xf bound_ctrl:1
	v_pk_fma_f32 v[4:5], v[4:5], v[154:155], v[178:179] op_sel:[0,1,0] op_sel_hi:[1,1,1]
	v_add_f32_dpp v198, v198, v198 quad_perm:[2,3,0,1] row_mask:0xf bank_mask:0xf bound_ctrl:1
	v_add_f32_dpp v199, v199, v199 quad_perm:[2,3,0,1] row_mask:0xf bank_mask:0xf bound_ctrl:1
	v_pk_fma_f32 v[6:7], v[6:7], v[156:157], v[180:181] op_sel:[0,0,0] op_sel_hi:[1,0,1]
	v_add_f32_dpp v198, v198, v198 row_half_mirror row_mask:0xf bank_mask:0xf bound_ctrl:1
	v_add_f32_dpp v199, v199, v199 row_half_mirror row_mask:0xf bank_mask:0xf bound_ctrl:1
	v_pk_fma_f32 v[8:9], v[8:9], v[156:157], v[188:189] op_sel:[0,1,0] op_sel_hi:[1,1,1]
	v_add_f32_dpp v198, v198, v198 row_mirror row_mask:0xf bank_mask:0xf bound_ctrl:1
	v_add_f32_dpp v199, v199, v199 row_mirror row_mask:0xf bank_mask:0xf bound_ctrl:1
	v_pk_fma_f32 v[2:3], v[158:159], v[198:199], v[2:3] op_sel:[0,0,0] op_sel_hi:[0,1,1] neg_lo:[0,1,0] neg_hi:[0,1,0]
	v_pk_fma_f32 v[4:5], v[158:159], v[198:199], v[4:5] op_sel:[1,0,0] op_sel_hi:[1,1,1] neg_lo:[0,1,0] neg_hi:[0,1,0]
	v_pk_fma_f32 v[6:7], v[160:161], v[198:199], v[6:7] op_sel:[0,0,0] op_sel_hi:[0,1,1] neg_lo:[0,1,0] neg_hi:[0,1,0]
	v_pk_fma_f32 v[8:9], v[160:161], v[198:199], v[8:9] op_sel:[1,0,0] op_sel_hi:[1,1,1] neg_lo:[0,1,0] neg_hi:[0,1,0]
	v_pk_mul_f32 v[24:25], v[2:3], v[170:171] op_sel:[0,0] op_sel_hi:[1,0]
	v_pk_fma_f32 v[24:25], v[4:5], v[170:171], v[24:25] op_sel:[0,1,0] op_sel_hi:[1,1,1]
	v_pk_fma_f32 v[24:25], v[6:7], v[172:173], v[24:25] op_sel:[0,0,0] op_sel_hi:[1,0,1]
	v_pk_fma_f32 v[24:25], v[8:9], v[172:173], v[24:25] op_sel:[0,1,0] op_sel_hi:[1,1,1]
	s_waitcnt lgkmcnt(0)
	ds_read_b128 v[166:169], v42 offset:14592
	ds_read_b128 v[162:165], v42 offset:14336
	ds_read_b64 v[174:175], v43 offset:13824
	ds_read_b128 v[154:157], v42 offset:13824
	ds_read_b128 v[158:161], v42 offset:14080
	ds_read_b128 v[170:173], v42 offset:14848
	v_pk_mul_f32 v[198:199], v[2:3], v[134:135] op_sel:[0,0] op_sel_hi:[1,0]
	v_pk_mul_f32 v[176:177], v[142:143], v[130:131] op_sel:[0,0] op_sel_hi:[1,0]
	v_pk_fma_f32 v[198:199], v[4:5], v[134:135], v[198:199] op_sel:[0,1,0] op_sel_hi:[1,1,1]
	v_pk_mul_f32 v[178:179], v[142:143], v[130:131] op_sel:[0,1] op_sel_hi:[1,1]
	v_pk_fma_f32 v[198:199], v[6:7], v[136:137], v[198:199] op_sel:[0,0,0] op_sel_hi:[1,0,1]
	v_pk_mul_f32 v[180:181], v[142:143], v[132:133] op_sel:[0,0] op_sel_hi:[1,0]
	v_pk_fma_f32 v[198:199], v[8:9], v[136:137], v[198:199] op_sel:[0,1,0] op_sel_hi:[1,1,1]
	v_pk_mul_f32 v[188:189], v[142:143], v[132:133] op_sel:[0,1] op_sel_hi:[1,1]
	v_pk_fma_f32 v[2:3], v[2:3], v[122:123], v[176:177] op_sel:[0,0,0] op_sel_hi:[1,0,1]
	v_add_f32_dpp v198, v198, v198 quad_perm:[1,0,3,2] row_mask:0xf bank_mask:0xf bound_ctrl:1
	v_add_f32_dpp v199, v199, v199 quad_perm:[1,0,3,2] row_mask:0xf bank_mask:0xf bound_ctrl:1
	v_pk_fma_f32 v[4:5], v[4:5], v[122:123], v[178:179] op_sel:[0,1,0] op_sel_hi:[1,1,1]
	v_add_f32_dpp v198, v198, v198 quad_perm:[2,3,0,1] row_mask:0xf bank_mask:0xf bound_ctrl:1
	v_add_f32_dpp v199, v199, v199 quad_perm:[2,3,0,1] row_mask:0xf bank_mask:0xf bound_ctrl:1
	v_pk_fma_f32 v[6:7], v[6:7], v[124:125], v[180:181] op_sel:[0,0,0] op_sel_hi:[1,0,1]
	v_add_f32_dpp v198, v198, v198 row_half_mirror row_mask:0xf bank_mask:0xf bound_ctrl:1
	v_add_f32_dpp v199, v199, v199 row_half_mirror row_mask:0xf bank_mask:0xf bound_ctrl:1
	v_pk_fma_f32 v[8:9], v[8:9], v[124:125], v[188:189] op_sel:[0,1,0] op_sel_hi:[1,1,1]
	v_add_f32_dpp v198, v198, v198 row_mirror row_mask:0xf bank_mask:0xf bound_ctrl:1
	v_add_f32_dpp v199, v199, v199 row_mirror row_mask:0xf bank_mask:0xf bound_ctrl:1
	v_pk_fma_f32 v[2:3], v[126:127], v[198:199], v[2:3] op_sel:[0,0,0] op_sel_hi:[0,1,1] neg_lo:[0,1,0] neg_hi:[0,1,0]
	v_pk_fma_f32 v[4:5], v[126:127], v[198:199], v[4:5] op_sel:[1,0,0] op_sel_hi:[1,1,1] neg_lo:[0,1,0] neg_hi:[0,1,0]
	v_pk_fma_f32 v[6:7], v[128:129], v[198:199], v[6:7] op_sel:[0,0,0] op_sel_hi:[0,1,1] neg_lo:[0,1,0] neg_hi:[0,1,0]
	v_pk_fma_f32 v[8:9], v[128:129], v[198:199], v[8:9] op_sel:[1,0,0] op_sel_hi:[1,1,1] neg_lo:[0,1,0] neg_hi:[0,1,0]
	v_pk_mul_f32 v[26:27], v[2:3], v[138:139] op_sel:[0,0] op_sel_hi:[1,0]
	v_pk_fma_f32 v[26:27], v[4:5], v[138:139], v[26:27] op_sel:[0,1,0] op_sel_hi:[1,1,1]
	v_pk_fma_f32 v[26:27], v[6:7], v[140:141], v[26:27] op_sel:[0,0,0] op_sel_hi:[1,0,1]
	v_pk_fma_f32 v[26:27], v[8:9], v[140:141], v[26:27] op_sel:[0,1,0] op_sel_hi:[1,1,1]
	s_waitcnt lgkmcnt(0)
	ds_read_b128 v[134:137], v42 offset:16128
	ds_read_b128 v[130:133], v42 offset:15872
	ds_read_b64 v[142:143], v43 offset:15360
	ds_read_b128 v[122:125], v42 offset:15360
	ds_read_b128 v[126:129], v42 offset:15616
	ds_read_b128 v[138:141], v42 offset:16384
	v_pk_mul_f32 v[198:199], v[2:3], v[166:167] op_sel:[0,0] op_sel_hi:[1,0]
	v_pk_mul_f32 v[176:177], v[174:175], v[162:163] op_sel:[0,0] op_sel_hi:[1,0]
	v_pk_fma_f32 v[198:199], v[4:5], v[166:167], v[198:199] op_sel:[0,1,0] op_sel_hi:[1,1,1]
	v_pk_mul_f32 v[178:179], v[174:175], v[162:163] op_sel:[0,1] op_sel_hi:[1,1]
	v_pk_fma_f32 v[198:199], v[6:7], v[168:169], v[198:199] op_sel:[0,0,0] op_sel_hi:[1,0,1]
	v_pk_mul_f32 v[180:181], v[174:175], v[164:165] op_sel:[0,0] op_sel_hi:[1,0]
	v_pk_fma_f32 v[198:199], v[8:9], v[168:169], v[198:199] op_sel:[0,1,0] op_sel_hi:[1,1,1]
	v_pk_mul_f32 v[188:189], v[174:175], v[164:165] op_sel:[0,1] op_sel_hi:[1,1]
	v_pk_fma_f32 v[2:3], v[2:3], v[154:155], v[176:177] op_sel:[0,0,0] op_sel_hi:[1,0,1]
	v_add_f32_dpp v198, v198, v198 quad_perm:[1,0,3,2] row_mask:0xf bank_mask:0xf bound_ctrl:1
	v_add_f32_dpp v199, v199, v199 quad_perm:[1,0,3,2] row_mask:0xf bank_mask:0xf bound_ctrl:1
	v_pk_fma_f32 v[4:5], v[4:5], v[154:155], v[178:179] op_sel:[0,1,0] op_sel_hi:[1,1,1]
	v_add_f32_dpp v198, v198, v198 quad_perm:[2,3,0,1] row_mask:0xf bank_mask:0xf bound_ctrl:1
	v_add_f32_dpp v199, v199, v199 quad_perm:[2,3,0,1] row_mask:0xf bank_mask:0xf bound_ctrl:1
	v_pk_fma_f32 v[6:7], v[6:7], v[156:157], v[180:181] op_sel:[0,0,0] op_sel_hi:[1,0,1]
	v_add_f32_dpp v198, v198, v198 row_half_mirror row_mask:0xf bank_mask:0xf bound_ctrl:1
	v_add_f32_dpp v199, v199, v199 row_half_mirror row_mask:0xf bank_mask:0xf bound_ctrl:1
	v_pk_fma_f32 v[8:9], v[8:9], v[156:157], v[188:189] op_sel:[0,1,0] op_sel_hi:[1,1,1]
	v_add_f32_dpp v198, v198, v198 row_mirror row_mask:0xf bank_mask:0xf bound_ctrl:1
	v_add_f32_dpp v199, v199, v199 row_mirror row_mask:0xf bank_mask:0xf bound_ctrl:1
	v_pk_fma_f32 v[2:3], v[158:159], v[198:199], v[2:3] op_sel:[0,0,0] op_sel_hi:[0,1,1] neg_lo:[0,1,0] neg_hi:[0,1,0]
	v_pk_fma_f32 v[4:5], v[158:159], v[198:199], v[4:5] op_sel:[1,0,0] op_sel_hi:[1,1,1] neg_lo:[0,1,0] neg_hi:[0,1,0]
	v_pk_fma_f32 v[6:7], v[160:161], v[198:199], v[6:7] op_sel:[0,0,0] op_sel_hi:[0,1,1] neg_lo:[0,1,0] neg_hi:[0,1,0]
	v_pk_fma_f32 v[8:9], v[160:161], v[198:199], v[8:9] op_sel:[1,0,0] op_sel_hi:[1,1,1] neg_lo:[0,1,0] neg_hi:[0,1,0]
	v_pk_mul_f32 v[28:29], v[2:3], v[170:171] op_sel:[0,0] op_sel_hi:[1,0]
	v_pk_fma_f32 v[28:29], v[4:5], v[170:171], v[28:29] op_sel:[0,1,0] op_sel_hi:[1,1,1]
	v_pk_fma_f32 v[28:29], v[6:7], v[172:173], v[28:29] op_sel:[0,0,0] op_sel_hi:[1,0,1]
	v_pk_fma_f32 v[28:29], v[8:9], v[172:173], v[28:29] op_sel:[0,1,0] op_sel_hi:[1,1,1]
	s_waitcnt lgkmcnt(0)
	ds_read_b128 v[166:169], v42 offset:17664
	ds_read_b128 v[162:165], v42 offset:17408
	ds_read_b64 v[174:175], v43 offset:16896
	ds_read_b128 v[154:157], v42 offset:16896
	ds_read_b128 v[158:161], v42 offset:17152
	ds_read_b128 v[170:173], v42 offset:17920
	v_pk_mul_f32 v[198:199], v[2:3], v[134:135] op_sel:[0,0] op_sel_hi:[1,0]
	v_pk_mul_f32 v[176:177], v[142:143], v[130:131] op_sel:[0,0] op_sel_hi:[1,0]
	v_pk_fma_f32 v[198:199], v[4:5], v[134:135], v[198:199] op_sel:[0,1,0] op_sel_hi:[1,1,1]
	v_pk_mul_f32 v[178:179], v[142:143], v[130:131] op_sel:[0,1] op_sel_hi:[1,1]
	v_pk_fma_f32 v[198:199], v[6:7], v[136:137], v[198:199] op_sel:[0,0,0] op_sel_hi:[1,0,1]
	v_pk_mul_f32 v[180:181], v[142:143], v[132:133] op_sel:[0,0] op_sel_hi:[1,0]
	v_pk_fma_f32 v[198:199], v[8:9], v[136:137], v[198:199] op_sel:[0,1,0] op_sel_hi:[1,1,1]
	v_pk_mul_f32 v[188:189], v[142:143], v[132:133] op_sel:[0,1] op_sel_hi:[1,1]
	v_pk_fma_f32 v[2:3], v[2:3], v[122:123], v[176:177] op_sel:[0,0,0] op_sel_hi:[1,0,1]
	v_add_f32_dpp v198, v198, v198 quad_perm:[1,0,3,2] row_mask:0xf bank_mask:0xf bound_ctrl:1
	v_add_f32_dpp v199, v199, v199 quad_perm:[1,0,3,2] row_mask:0xf bank_mask:0xf bound_ctrl:1
	v_pk_fma_f32 v[4:5], v[4:5], v[122:123], v[178:179] op_sel:[0,1,0] op_sel_hi:[1,1,1]
	v_add_f32_dpp v198, v198, v198 quad_perm:[2,3,0,1] row_mask:0xf bank_mask:0xf bound_ctrl:1
	v_add_f32_dpp v199, v199, v199 quad_perm:[2,3,0,1] row_mask:0xf bank_mask:0xf bound_ctrl:1
	v_pk_fma_f32 v[6:7], v[6:7], v[124:125], v[180:181] op_sel:[0,0,0] op_sel_hi:[1,0,1]
	v_add_f32_dpp v198, v198, v198 row_half_mirror row_mask:0xf bank_mask:0xf bound_ctrl:1
	v_add_f32_dpp v199, v199, v199 row_half_mirror row_mask:0xf bank_mask:0xf bound_ctrl:1
	v_pk_fma_f32 v[8:9], v[8:9], v[124:125], v[188:189] op_sel:[0,1,0] op_sel_hi:[1,1,1]
	v_add_f32_dpp v198, v198, v198 row_mirror row_mask:0xf bank_mask:0xf bound_ctrl:1
	v_add_f32_dpp v199, v199, v199 row_mirror row_mask:0xf bank_mask:0xf bound_ctrl:1
	v_pk_fma_f32 v[2:3], v[126:127], v[198:199], v[2:3] op_sel:[0,0,0] op_sel_hi:[0,1,1] neg_lo:[0,1,0] neg_hi:[0,1,0]
	v_pk_fma_f32 v[4:5], v[126:127], v[198:199], v[4:5] op_sel:[1,0,0] op_sel_hi:[1,1,1] neg_lo:[0,1,0] neg_hi:[0,1,0]
	v_pk_fma_f32 v[6:7], v[128:129], v[198:199], v[6:7] op_sel:[0,0,0] op_sel_hi:[0,1,1] neg_lo:[0,1,0] neg_hi:[0,1,0]
	v_pk_fma_f32 v[8:9], v[128:129], v[198:199], v[8:9] op_sel:[1,0,0] op_sel_hi:[1,1,1] neg_lo:[0,1,0] neg_hi:[0,1,0]
	v_pk_mul_f32 v[30:31], v[2:3], v[138:139] op_sel:[0,0] op_sel_hi:[1,0]
	v_pk_fma_f32 v[30:31], v[4:5], v[138:139], v[30:31] op_sel:[0,1,0] op_sel_hi:[1,1,1]
	v_pk_fma_f32 v[30:31], v[6:7], v[140:141], v[30:31] op_sel:[0,0,0] op_sel_hi:[1,0,1]
	v_pk_fma_f32 v[30:31], v[8:9], v[140:141], v[30:31] op_sel:[0,1,0] op_sel_hi:[1,1,1]
	s_waitcnt lgkmcnt(0)
	ds_read_b128 v[134:137], v42 offset:19200
	ds_read_b128 v[130:133], v42 offset:18944
	ds_read_b64 v[142:143], v43 offset:18432
	ds_read_b128 v[122:125], v42 offset:18432
	ds_read_b128 v[126:129], v42 offset:18688
	ds_read_b128 v[138:141], v42 offset:19456
	v_pk_mul_f32 v[198:199], v[2:3], v[166:167] op_sel:[0,0] op_sel_hi:[1,0]
	v_pk_mul_f32 v[176:177], v[174:175], v[162:163] op_sel:[0,0] op_sel_hi:[1,0]
	v_pk_fma_f32 v[198:199], v[4:5], v[166:167], v[198:199] op_sel:[0,1,0] op_sel_hi:[1,1,1]
	v_pk_mul_f32 v[178:179], v[174:175], v[162:163] op_sel:[0,1] op_sel_hi:[1,1]
	v_pk_fma_f32 v[198:199], v[6:7], v[168:169], v[198:199] op_sel:[0,0,0] op_sel_hi:[1,0,1]
	v_pk_mul_f32 v[180:181], v[174:175], v[164:165] op_sel:[0,0] op_sel_hi:[1,0]
	v_pk_fma_f32 v[198:199], v[8:9], v[168:169], v[198:199] op_sel:[0,1,0] op_sel_hi:[1,1,1]
	v_pk_mul_f32 v[188:189], v[174:175], v[164:165] op_sel:[0,1] op_sel_hi:[1,1]
	v_pk_fma_f32 v[2:3], v[2:3], v[154:155], v[176:177] op_sel:[0,0,0] op_sel_hi:[1,0,1]
	v_add_f32_dpp v198, v198, v198 quad_perm:[1,0,3,2] row_mask:0xf bank_mask:0xf bound_ctrl:1
	v_add_f32_dpp v199, v199, v199 quad_perm:[1,0,3,2] row_mask:0xf bank_mask:0xf bound_ctrl:1
	v_pk_fma_f32 v[4:5], v[4:5], v[154:155], v[178:179] op_sel:[0,1,0] op_sel_hi:[1,1,1]
	v_add_f32_dpp v198, v198, v198 quad_perm:[2,3,0,1] row_mask:0xf bank_mask:0xf bound_ctrl:1
	v_add_f32_dpp v199, v199, v199 quad_perm:[2,3,0,1] row_mask:0xf bank_mask:0xf bound_ctrl:1
	v_pk_fma_f32 v[6:7], v[6:7], v[156:157], v[180:181] op_sel:[0,0,0] op_sel_hi:[1,0,1]
	v_add_f32_dpp v198, v198, v198 row_half_mirror row_mask:0xf bank_mask:0xf bound_ctrl:1
	v_add_f32_dpp v199, v199, v199 row_half_mirror row_mask:0xf bank_mask:0xf bound_ctrl:1
	v_pk_fma_f32 v[8:9], v[8:9], v[156:157], v[188:189] op_sel:[0,1,0] op_sel_hi:[1,1,1]
	v_add_f32_dpp v198, v198, v198 row_mirror row_mask:0xf bank_mask:0xf bound_ctrl:1
	v_add_f32_dpp v199, v199, v199 row_mirror row_mask:0xf bank_mask:0xf bound_ctrl:1
	v_pk_fma_f32 v[2:3], v[158:159], v[198:199], v[2:3] op_sel:[0,0,0] op_sel_hi:[0,1,1] neg_lo:[0,1,0] neg_hi:[0,1,0]
	v_pk_fma_f32 v[4:5], v[158:159], v[198:199], v[4:5] op_sel:[1,0,0] op_sel_hi:[1,1,1] neg_lo:[0,1,0] neg_hi:[0,1,0]
	v_pk_fma_f32 v[6:7], v[160:161], v[198:199], v[6:7] op_sel:[0,0,0] op_sel_hi:[0,1,1] neg_lo:[0,1,0] neg_hi:[0,1,0]
	v_pk_fma_f32 v[8:9], v[160:161], v[198:199], v[8:9] op_sel:[1,0,0] op_sel_hi:[1,1,1] neg_lo:[0,1,0] neg_hi:[0,1,0]
	v_pk_mul_f32 v[32:33], v[2:3], v[170:171] op_sel:[0,0] op_sel_hi:[1,0]
	v_pk_fma_f32 v[32:33], v[4:5], v[170:171], v[32:33] op_sel:[0,1,0] op_sel_hi:[1,1,1]
	v_pk_fma_f32 v[32:33], v[6:7], v[172:173], v[32:33] op_sel:[0,0,0] op_sel_hi:[1,0,1]
	v_pk_fma_f32 v[32:33], v[8:9], v[172:173], v[32:33] op_sel:[0,1,0] op_sel_hi:[1,1,1]
	s_waitcnt lgkmcnt(0)
	ds_read_b128 v[166:169], v42 offset:20736
	ds_read_b128 v[162:165], v42 offset:20480
	ds_read_b64 v[174:175], v43 offset:19968
	ds_read_b128 v[154:157], v42 offset:19968
	ds_read_b128 v[158:161], v42 offset:20224
	ds_read_b128 v[170:173], v42 offset:20992
	v_pk_mul_f32 v[198:199], v[2:3], v[134:135] op_sel:[0,0] op_sel_hi:[1,0]
	v_pk_mul_f32 v[176:177], v[142:143], v[130:131] op_sel:[0,0] op_sel_hi:[1,0]
	v_pk_fma_f32 v[198:199], v[4:5], v[134:135], v[198:199] op_sel:[0,1,0] op_sel_hi:[1,1,1]
	v_pk_mul_f32 v[178:179], v[142:143], v[130:131] op_sel:[0,1] op_sel_hi:[1,1]
	v_pk_fma_f32 v[198:199], v[6:7], v[136:137], v[198:199] op_sel:[0,0,0] op_sel_hi:[1,0,1]
	v_pk_mul_f32 v[180:181], v[142:143], v[132:133] op_sel:[0,0] op_sel_hi:[1,0]
	v_pk_fma_f32 v[198:199], v[8:9], v[136:137], v[198:199] op_sel:[0,1,0] op_sel_hi:[1,1,1]
	v_pk_mul_f32 v[188:189], v[142:143], v[132:133] op_sel:[0,1] op_sel_hi:[1,1]
	v_pk_fma_f32 v[2:3], v[2:3], v[122:123], v[176:177] op_sel:[0,0,0] op_sel_hi:[1,0,1]
	v_add_f32_dpp v198, v198, v198 quad_perm:[1,0,3,2] row_mask:0xf bank_mask:0xf bound_ctrl:1
	v_add_f32_dpp v199, v199, v199 quad_perm:[1,0,3,2] row_mask:0xf bank_mask:0xf bound_ctrl:1
	v_pk_fma_f32 v[4:5], v[4:5], v[122:123], v[178:179] op_sel:[0,1,0] op_sel_hi:[1,1,1]
	v_add_f32_dpp v198, v198, v198 quad_perm:[2,3,0,1] row_mask:0xf bank_mask:0xf bound_ctrl:1
	v_add_f32_dpp v199, v199, v199 quad_perm:[2,3,0,1] row_mask:0xf bank_mask:0xf bound_ctrl:1
	v_pk_fma_f32 v[6:7], v[6:7], v[124:125], v[180:181] op_sel:[0,0,0] op_sel_hi:[1,0,1]
	v_add_f32_dpp v198, v198, v198 row_half_mirror row_mask:0xf bank_mask:0xf bound_ctrl:1
	v_add_f32_dpp v199, v199, v199 row_half_mirror row_mask:0xf bank_mask:0xf bound_ctrl:1
	v_pk_fma_f32 v[8:9], v[8:9], v[124:125], v[188:189] op_sel:[0,1,0] op_sel_hi:[1,1,1]
	v_add_f32_dpp v198, v198, v198 row_mirror row_mask:0xf bank_mask:0xf bound_ctrl:1
	v_add_f32_dpp v199, v199, v199 row_mirror row_mask:0xf bank_mask:0xf bound_ctrl:1
	v_pk_fma_f32 v[2:3], v[126:127], v[198:199], v[2:3] op_sel:[0,0,0] op_sel_hi:[0,1,1] neg_lo:[0,1,0] neg_hi:[0,1,0]
	v_pk_fma_f32 v[4:5], v[126:127], v[198:199], v[4:5] op_sel:[1,0,0] op_sel_hi:[1,1,1] neg_lo:[0,1,0] neg_hi:[0,1,0]
	v_pk_fma_f32 v[6:7], v[128:129], v[198:199], v[6:7] op_sel:[0,0,0] op_sel_hi:[0,1,1] neg_lo:[0,1,0] neg_hi:[0,1,0]
	v_pk_fma_f32 v[8:9], v[128:129], v[198:199], v[8:9] op_sel:[1,0,0] op_sel_hi:[1,1,1] neg_lo:[0,1,0] neg_hi:[0,1,0]
	v_pk_mul_f32 v[34:35], v[2:3], v[138:139] op_sel:[0,0] op_sel_hi:[1,0]
	v_pk_fma_f32 v[34:35], v[4:5], v[138:139], v[34:35] op_sel:[0,1,0] op_sel_hi:[1,1,1]
	v_pk_fma_f32 v[34:35], v[6:7], v[140:141], v[34:35] op_sel:[0,0,0] op_sel_hi:[1,0,1]
	v_pk_fma_f32 v[34:35], v[8:9], v[140:141], v[34:35] op_sel:[0,1,0] op_sel_hi:[1,1,1]
	s_waitcnt lgkmcnt(0)
	ds_read_b128 v[134:137], v42 offset:22272
	ds_read_b128 v[130:133], v42 offset:22016
	ds_read_b64 v[142:143], v43 offset:21504
	ds_read_b128 v[122:125], v42 offset:21504
	ds_read_b128 v[126:129], v42 offset:21760
	ds_read_b128 v[138:141], v42 offset:22528
	v_pk_mul_f32 v[198:199], v[2:3], v[166:167] op_sel:[0,0] op_sel_hi:[1,0]
	v_pk_mul_f32 v[176:177], v[174:175], v[162:163] op_sel:[0,0] op_sel_hi:[1,0]
	v_pk_fma_f32 v[198:199], v[4:5], v[166:167], v[198:199] op_sel:[0,1,0] op_sel_hi:[1,1,1]
	v_pk_mul_f32 v[178:179], v[174:175], v[162:163] op_sel:[0,1] op_sel_hi:[1,1]
	v_pk_fma_f32 v[198:199], v[6:7], v[168:169], v[198:199] op_sel:[0,0,0] op_sel_hi:[1,0,1]
	v_pk_mul_f32 v[180:181], v[174:175], v[164:165] op_sel:[0,0] op_sel_hi:[1,0]
	v_pk_fma_f32 v[198:199], v[8:9], v[168:169], v[198:199] op_sel:[0,1,0] op_sel_hi:[1,1,1]
	v_pk_mul_f32 v[188:189], v[174:175], v[164:165] op_sel:[0,1] op_sel_hi:[1,1]
	v_pk_fma_f32 v[2:3], v[2:3], v[154:155], v[176:177] op_sel:[0,0,0] op_sel_hi:[1,0,1]
	v_add_f32_dpp v198, v198, v198 quad_perm:[1,0,3,2] row_mask:0xf bank_mask:0xf bound_ctrl:1
	v_add_f32_dpp v199, v199, v199 quad_perm:[1,0,3,2] row_mask:0xf bank_mask:0xf bound_ctrl:1
	v_pk_fma_f32 v[4:5], v[4:5], v[154:155], v[178:179] op_sel:[0,1,0] op_sel_hi:[1,1,1]
	v_add_f32_dpp v198, v198, v198 quad_perm:[2,3,0,1] row_mask:0xf bank_mask:0xf bound_ctrl:1
	v_add_f32_dpp v199, v199, v199 quad_perm:[2,3,0,1] row_mask:0xf bank_mask:0xf bound_ctrl:1
	v_pk_fma_f32 v[6:7], v[6:7], v[156:157], v[180:181] op_sel:[0,0,0] op_sel_hi:[1,0,1]
	v_add_f32_dpp v198, v198, v198 row_half_mirror row_mask:0xf bank_mask:0xf bound_ctrl:1
	v_add_f32_dpp v199, v199, v199 row_half_mirror row_mask:0xf bank_mask:0xf bound_ctrl:1
	v_pk_fma_f32 v[8:9], v[8:9], v[156:157], v[188:189] op_sel:[0,1,0] op_sel_hi:[1,1,1]
	v_add_f32_dpp v198, v198, v198 row_mirror row_mask:0xf bank_mask:0xf bound_ctrl:1
	v_add_f32_dpp v199, v199, v199 row_mirror row_mask:0xf bank_mask:0xf bound_ctrl:1
	v_pk_fma_f32 v[2:3], v[158:159], v[198:199], v[2:3] op_sel:[0,0,0] op_sel_hi:[0,1,1] neg_lo:[0,1,0] neg_hi:[0,1,0]
	v_pk_fma_f32 v[4:5], v[158:159], v[198:199], v[4:5] op_sel:[1,0,0] op_sel_hi:[1,1,1] neg_lo:[0,1,0] neg_hi:[0,1,0]
	v_pk_fma_f32 v[6:7], v[160:161], v[198:199], v[6:7] op_sel:[0,0,0] op_sel_hi:[0,1,1] neg_lo:[0,1,0] neg_hi:[0,1,0]
	v_pk_fma_f32 v[8:9], v[160:161], v[198:199], v[8:9] op_sel:[1,0,0] op_sel_hi:[1,1,1] neg_lo:[0,1,0] neg_hi:[0,1,0]
	v_pk_mul_f32 v[36:37], v[2:3], v[170:171] op_sel:[0,0] op_sel_hi:[1,0]
	v_pk_fma_f32 v[36:37], v[4:5], v[170:171], v[36:37] op_sel:[0,1,0] op_sel_hi:[1,1,1]
	v_pk_fma_f32 v[36:37], v[6:7], v[172:173], v[36:37] op_sel:[0,0,0] op_sel_hi:[1,0,1]
	v_pk_fma_f32 v[36:37], v[8:9], v[172:173], v[36:37] op_sel:[0,1,0] op_sel_hi:[1,1,1]
	s_waitcnt lgkmcnt(0)
	ds_read_b128 v[166:169], v42 offset:23808
	ds_read_b128 v[162:165], v42 offset:23552
	ds_read_b64 v[174:175], v43 offset:23040
	ds_read_b128 v[154:157], v42 offset:23040
	ds_read_b128 v[158:161], v42 offset:23296
	ds_read_b128 v[170:173], v42 offset:24064
	v_pk_mul_f32 v[198:199], v[2:3], v[134:135] op_sel:[0,0] op_sel_hi:[1,0]
	v_pk_mul_f32 v[176:177], v[142:143], v[130:131] op_sel:[0,0] op_sel_hi:[1,0]
	v_pk_fma_f32 v[198:199], v[4:5], v[134:135], v[198:199] op_sel:[0,1,0] op_sel_hi:[1,1,1]
	v_pk_mul_f32 v[178:179], v[142:143], v[130:131] op_sel:[0,1] op_sel_hi:[1,1]
	v_pk_fma_f32 v[198:199], v[6:7], v[136:137], v[198:199] op_sel:[0,0,0] op_sel_hi:[1,0,1]
	v_pk_mul_f32 v[180:181], v[142:143], v[132:133] op_sel:[0,0] op_sel_hi:[1,0]
	v_pk_fma_f32 v[198:199], v[8:9], v[136:137], v[198:199] op_sel:[0,1,0] op_sel_hi:[1,1,1]
	v_pk_mul_f32 v[188:189], v[142:143], v[132:133] op_sel:[0,1] op_sel_hi:[1,1]
	v_pk_fma_f32 v[2:3], v[2:3], v[122:123], v[176:177] op_sel:[0,0,0] op_sel_hi:[1,0,1]
	v_add_f32_dpp v198, v198, v198 quad_perm:[1,0,3,2] row_mask:0xf bank_mask:0xf bound_ctrl:1
	v_add_f32_dpp v199, v199, v199 quad_perm:[1,0,3,2] row_mask:0xf bank_mask:0xf bound_ctrl:1
	v_pk_fma_f32 v[4:5], v[4:5], v[122:123], v[178:179] op_sel:[0,1,0] op_sel_hi:[1,1,1]
	v_add_f32_dpp v198, v198, v198 quad_perm:[2,3,0,1] row_mask:0xf bank_mask:0xf bound_ctrl:1
	v_add_f32_dpp v199, v199, v199 quad_perm:[2,3,0,1] row_mask:0xf bank_mask:0xf bound_ctrl:1
	v_pk_fma_f32 v[6:7], v[6:7], v[124:125], v[180:181] op_sel:[0,0,0] op_sel_hi:[1,0,1]
	v_add_f32_dpp v198, v198, v198 row_half_mirror row_mask:0xf bank_mask:0xf bound_ctrl:1
	v_add_f32_dpp v199, v199, v199 row_half_mirror row_mask:0xf bank_mask:0xf bound_ctrl:1
	v_pk_fma_f32 v[8:9], v[8:9], v[124:125], v[188:189] op_sel:[0,1,0] op_sel_hi:[1,1,1]
	v_add_f32_dpp v198, v198, v198 row_mirror row_mask:0xf bank_mask:0xf bound_ctrl:1
	v_add_f32_dpp v199, v199, v199 row_mirror row_mask:0xf bank_mask:0xf bound_ctrl:1
	v_pk_fma_f32 v[2:3], v[126:127], v[198:199], v[2:3] op_sel:[0,0,0] op_sel_hi:[0,1,1] neg_lo:[0,1,0] neg_hi:[0,1,0]
	v_pk_fma_f32 v[4:5], v[126:127], v[198:199], v[4:5] op_sel:[1,0,0] op_sel_hi:[1,1,1] neg_lo:[0,1,0] neg_hi:[0,1,0]
	v_pk_fma_f32 v[6:7], v[128:129], v[198:199], v[6:7] op_sel:[0,0,0] op_sel_hi:[0,1,1] neg_lo:[0,1,0] neg_hi:[0,1,0]
	v_pk_fma_f32 v[8:9], v[128:129], v[198:199], v[8:9] op_sel:[1,0,0] op_sel_hi:[1,1,1] neg_lo:[0,1,0] neg_hi:[0,1,0]
	v_pk_mul_f32 v[38:39], v[2:3], v[138:139] op_sel:[0,0] op_sel_hi:[1,0]
	v_pk_fma_f32 v[38:39], v[4:5], v[138:139], v[38:39] op_sel:[0,1,0] op_sel_hi:[1,1,1]
	v_pk_fma_f32 v[38:39], v[6:7], v[140:141], v[38:39] op_sel:[0,0,0] op_sel_hi:[1,0,1]
	v_pk_fma_f32 v[38:39], v[8:9], v[140:141], v[38:39] op_sel:[0,1,0] op_sel_hi:[1,1,1]
	s_waitcnt lgkmcnt(0)
	ds_read_b128 v[134:137], v42 offset:25344
	ds_read_b128 v[130:133], v42 offset:25088
	ds_read_b64 v[142:143], v43 offset:24576
	ds_read_b128 v[122:125], v42 offset:24576
	ds_read_b128 v[126:129], v42 offset:24832
	ds_read_b128 v[138:141], v42 offset:25600
	v_pk_mul_f32 v[198:199], v[2:3], v[166:167] op_sel:[0,0] op_sel_hi:[1,0]
	v_pk_mul_f32 v[176:177], v[174:175], v[162:163] op_sel:[0,0] op_sel_hi:[1,0]
	v_pk_fma_f32 v[198:199], v[4:5], v[166:167], v[198:199] op_sel:[0,1,0] op_sel_hi:[1,1,1]
	v_pk_mul_f32 v[178:179], v[174:175], v[162:163] op_sel:[0,1] op_sel_hi:[1,1]
	v_pk_fma_f32 v[198:199], v[6:7], v[168:169], v[198:199] op_sel:[0,0,0] op_sel_hi:[1,0,1]
	v_pk_mul_f32 v[180:181], v[174:175], v[164:165] op_sel:[0,0] op_sel_hi:[1,0]
	v_pk_fma_f32 v[198:199], v[8:9], v[168:169], v[198:199] op_sel:[0,1,0] op_sel_hi:[1,1,1]
	v_pk_mul_f32 v[188:189], v[174:175], v[164:165] op_sel:[0,1] op_sel_hi:[1,1]
	v_pk_fma_f32 v[2:3], v[2:3], v[154:155], v[176:177] op_sel:[0,0,0] op_sel_hi:[1,0,1]
	v_add_f32_dpp v198, v198, v198 quad_perm:[1,0,3,2] row_mask:0xf bank_mask:0xf bound_ctrl:1
	v_add_f32_dpp v199, v199, v199 quad_perm:[1,0,3,2] row_mask:0xf bank_mask:0xf bound_ctrl:1
	v_pk_fma_f32 v[4:5], v[4:5], v[154:155], v[178:179] op_sel:[0,1,0] op_sel_hi:[1,1,1]
	v_add_f32_dpp v198, v198, v198 quad_perm:[2,3,0,1] row_mask:0xf bank_mask:0xf bound_ctrl:1
	v_add_f32_dpp v199, v199, v199 quad_perm:[2,3,0,1] row_mask:0xf bank_mask:0xf bound_ctrl:1
	v_pk_fma_f32 v[6:7], v[6:7], v[156:157], v[180:181] op_sel:[0,0,0] op_sel_hi:[1,0,1]
	v_add_f32_dpp v198, v198, v198 row_half_mirror row_mask:0xf bank_mask:0xf bound_ctrl:1
	v_add_f32_dpp v199, v199, v199 row_half_mirror row_mask:0xf bank_mask:0xf bound_ctrl:1
	v_pk_fma_f32 v[8:9], v[8:9], v[156:157], v[188:189] op_sel:[0,1,0] op_sel_hi:[1,1,1]
	v_add_f32_dpp v198, v198, v198 row_mirror row_mask:0xf bank_mask:0xf bound_ctrl:1
	v_add_f32_dpp v199, v199, v199 row_mirror row_mask:0xf bank_mask:0xf bound_ctrl:1
	v_pk_fma_f32 v[2:3], v[158:159], v[198:199], v[2:3] op_sel:[0,0,0] op_sel_hi:[0,1,1] neg_lo:[0,1,0] neg_hi:[0,1,0]
	v_pk_fma_f32 v[4:5], v[158:159], v[198:199], v[4:5] op_sel:[1,0,0] op_sel_hi:[1,1,1] neg_lo:[0,1,0] neg_hi:[0,1,0]
	v_pk_fma_f32 v[6:7], v[160:161], v[198:199], v[6:7] op_sel:[0,0,0] op_sel_hi:[0,1,1] neg_lo:[0,1,0] neg_hi:[0,1,0]
	v_pk_fma_f32 v[8:9], v[160:161], v[198:199], v[8:9] op_sel:[1,0,0] op_sel_hi:[1,1,1] neg_lo:[0,1,0] neg_hi:[0,1,0]
	v_pk_mul_f32 v[40:41], v[2:3], v[170:171] op_sel:[0,0] op_sel_hi:[1,0]
	v_pk_fma_f32 v[40:41], v[4:5], v[170:171], v[40:41] op_sel:[0,1,0] op_sel_hi:[1,1,1]
	v_pk_fma_f32 v[40:41], v[6:7], v[172:173], v[40:41] op_sel:[0,0,0] op_sel_hi:[1,0,1]
	v_pk_fma_f32 v[40:41], v[8:9], v[172:173], v[40:41] op_sel:[0,1,0] op_sel_hi:[1,1,1]
	v_add_f32_dpp v190, v10, v10 row_mirror row_mask:0xf bank_mask:0x3
	v_add_f32_dpp v190, v26, v26 row_mirror row_mask:0xf bank_mask:0xc
	v_add_f32_dpp v191, v12, v12 row_mirror row_mask:0xf bank_mask:0x3
	v_add_f32_dpp v191, v28, v28 row_mirror row_mask:0xf bank_mask:0xc
	v_add_f32_dpp v192, v14, v14 row_mirror row_mask:0xf bank_mask:0x3
	v_add_f32_dpp v192, v30, v30 row_mirror row_mask:0xf bank_mask:0xc
	v_add_f32_dpp v193, v16, v16 row_mirror row_mask:0xf bank_mask:0x3
	v_add_f32_dpp v193, v32, v32 row_mirror row_mask:0xf bank_mask:0xc
	v_add_f32_dpp v194, v18, v18 row_mirror row_mask:0xf bank_mask:0x3
	v_add_f32_dpp v194, v34, v34 row_mirror row_mask:0xf bank_mask:0xc
	v_add_f32_dpp v195, v20, v20 row_mirror row_mask:0xf bank_mask:0x3
	v_add_f32_dpp v195, v36, v36 row_mirror row_mask:0xf bank_mask:0xc
	v_add_f32_dpp v196, v22, v22 row_mirror row_mask:0xf bank_mask:0x3
	v_add_f32_dpp v196, v38, v38 row_mirror row_mask:0xf bank_mask:0xc
	v_add_f32_dpp v197, v24, v24 row_mirror row_mask:0xf bank_mask:0x3
	v_add_f32_dpp v197, v40, v40 row_mirror row_mask:0xf bank_mask:0xc
	v_add_f32_dpp v202, v190, v190 row_half_mirror row_mask:0xf bank_mask:0x5
	v_add_f32_dpp v202, v194, v194 row_half_mirror row_mask:0xf bank_mask:0xa
	v_add_f32_dpp v203, v191, v191 row_half_mirror row_mask:0xf bank_mask:0x5
	v_add_f32_dpp v203, v195, v195 row_half_mirror row_mask:0xf bank_mask:0xa
	v_add_f32_dpp v204, v192, v192 row_half_mirror row_mask:0xf bank_mask:0x5
	v_add_f32_dpp v204, v196, v196 row_half_mirror row_mask:0xf bank_mask:0xa
	v_add_f32_dpp v205, v193, v193 row_half_mirror row_mask:0xf bank_mask:0x5
	v_add_f32_dpp v205, v197, v197 row_half_mirror row_mask:0xf bank_mask:0xa
	v_cndmask_b32_e64 v176, v202, v204, s[84:85]
	v_cndmask_b32_e64 v177, v204, v202, s[84:85]
	v_cndmask_b32_e64 v178, v203, v205, s[84:85]
	v_cndmask_b32_e64 v179, v205, v203, s[84:85]
	s_nop 1
	v_add_f32_dpp v210, v177, v176 quad_perm:[2,3,0,1] row_mask:0xf bank_mask:0xf bound_ctrl:1
	v_add_f32_dpp v211, v179, v178 quad_perm:[2,3,0,1] row_mask:0xf bank_mask:0xf bound_ctrl:1
	s_nop 0
	v_cndmask_b32_e64 v176, v210, v211, s[88:89]
	v_cndmask_b32_e64 v177, v211, v210, s[88:89]
	s_nop 1
	v_add_f32_dpp v212, v177, v176 quad_perm:[1,0,3,2] row_mask:0xf bank_mask:0xf bound_ctrl:1
	ds_write_b32 v44, v212 offset:0
	v_add_f32_dpp v190, v11, v11 row_mirror row_mask:0xf bank_mask:0x3
	v_add_f32_dpp v190, v27, v27 row_mirror row_mask:0xf bank_mask:0xc
	v_add_f32_dpp v191, v13, v13 row_mirror row_mask:0xf bank_mask:0x3
	v_add_f32_dpp v191, v29, v29 row_mirror row_mask:0xf bank_mask:0xc
	v_add_f32_dpp v192, v15, v15 row_mirror row_mask:0xf bank_mask:0x3
	v_add_f32_dpp v192, v31, v31 row_mirror row_mask:0xf bank_mask:0xc
	v_add_f32_dpp v193, v17, v17 row_mirror row_mask:0xf bank_mask:0x3
	v_add_f32_dpp v193, v33, v33 row_mirror row_mask:0xf bank_mask:0xc
	v_add_f32_dpp v194, v19, v19 row_mirror row_mask:0xf bank_mask:0x3
	v_add_f32_dpp v194, v35, v35 row_mirror row_mask:0xf bank_mask:0xc
	v_add_f32_dpp v195, v21, v21 row_mirror row_mask:0xf bank_mask:0x3
	v_add_f32_dpp v195, v37, v37 row_mirror row_mask:0xf bank_mask:0xc
	v_add_f32_dpp v196, v23, v23 row_mirror row_mask:0xf bank_mask:0x3
	v_add_f32_dpp v196, v39, v39 row_mirror row_mask:0xf bank_mask:0xc
	v_add_f32_dpp v197, v25, v25 row_mirror row_mask:0xf bank_mask:0x3
	v_add_f32_dpp v197, v41, v41 row_mirror row_mask:0xf bank_mask:0xc
	v_add_f32_dpp v202, v190, v190 row_half_mirror row_mask:0xf bank_mask:0x5
	v_add_f32_dpp v202, v194, v194 row_half_mirror row_mask:0xf bank_mask:0xa
	v_add_f32_dpp v203, v191, v191 row_half_mirror row_mask:0xf bank_mask:0x5
	v_add_f32_dpp v203, v195, v195 row_half_mirror row_mask:0xf bank_mask:0xa
	v_add_f32_dpp v204, v192, v192 row_half_mirror row_mask:0xf bank_mask:0x5
	v_add_f32_dpp v204, v196, v196 row_half_mirror row_mask:0xf bank_mask:0xa
	v_add_f32_dpp v205, v193, v193 row_half_mirror row_mask:0xf bank_mask:0x5
	v_add_f32_dpp v205, v197, v197 row_half_mirror row_mask:0xf bank_mask:0xa
	v_cndmask_b32_e64 v176, v202, v204, s[84:85]
	v_cndmask_b32_e64 v177, v204, v202, s[84:85]
	v_cndmask_b32_e64 v178, v203, v205, s[84:85]
	v_cndmask_b32_e64 v179, v205, v203, s[84:85]
	s_nop 1
	v_add_f32_dpp v210, v177, v176 quad_perm:[2,3,0,1] row_mask:0xf bank_mask:0xf bound_ctrl:1
	v_add_f32_dpp v211, v179, v178 quad_perm:[2,3,0,1] row_mask:0xf bank_mask:0xf bound_ctrl:1
	s_nop 0
	v_cndmask_b32_e64 v176, v210, v211, s[88:89]
	v_cndmask_b32_e64 v177, v211, v210, s[88:89]
	s_nop 1
	v_add_f32_dpp v212, v177, v176 quad_perm:[1,0,3,2] row_mask:0xf bank_mask:0xf bound_ctrl:1
	ds_write_b32 v44, v212 offset:4
	s_waitcnt lgkmcnt(2)
	ds_read_b128 v[166:169], v42 offset:26880
	ds_read_b128 v[162:165], v42 offset:26624
	ds_read_b64 v[174:175], v43 offset:26112
	ds_read_b128 v[154:157], v42 offset:26112
	ds_read_b128 v[158:161], v42 offset:26368
	ds_read_b128 v[170:173], v42 offset:27136
	v_pk_mul_f32 v[198:199], v[2:3], v[134:135] op_sel:[0,0] op_sel_hi:[1,0]
	v_pk_mul_f32 v[176:177], v[142:143], v[130:131] op_sel:[0,0] op_sel_hi:[1,0]
	v_pk_fma_f32 v[198:199], v[4:5], v[134:135], v[198:199] op_sel:[0,1,0] op_sel_hi:[1,1,1]
	v_pk_mul_f32 v[178:179], v[142:143], v[130:131] op_sel:[0,1] op_sel_hi:[1,1]
	v_pk_fma_f32 v[198:199], v[6:7], v[136:137], v[198:199] op_sel:[0,0,0] op_sel_hi:[1,0,1]
	v_pk_mul_f32 v[180:181], v[142:143], v[132:133] op_sel:[0,0] op_sel_hi:[1,0]
	v_pk_fma_f32 v[198:199], v[8:9], v[136:137], v[198:199] op_sel:[0,1,0] op_sel_hi:[1,1,1]
	v_pk_mul_f32 v[188:189], v[142:143], v[132:133] op_sel:[0,1] op_sel_hi:[1,1]
	v_pk_fma_f32 v[2:3], v[2:3], v[122:123], v[176:177] op_sel:[0,0,0] op_sel_hi:[1,0,1]
	v_add_f32_dpp v198, v198, v198 quad_perm:[1,0,3,2] row_mask:0xf bank_mask:0xf bound_ctrl:1
	v_add_f32_dpp v199, v199, v199 quad_perm:[1,0,3,2] row_mask:0xf bank_mask:0xf bound_ctrl:1
	v_pk_fma_f32 v[4:5], v[4:5], v[122:123], v[178:179] op_sel:[0,1,0] op_sel_hi:[1,1,1]
	v_add_f32_dpp v198, v198, v198 quad_perm:[2,3,0,1] row_mask:0xf bank_mask:0xf bound_ctrl:1
	v_add_f32_dpp v199, v199, v199 quad_perm:[2,3,0,1] row_mask:0xf bank_mask:0xf bound_ctrl:1
	v_pk_fma_f32 v[6:7], v[6:7], v[124:125], v[180:181] op_sel:[0,0,0] op_sel_hi:[1,0,1]
	v_add_f32_dpp v198, v198, v198 row_half_mirror row_mask:0xf bank_mask:0xf bound_ctrl:1
	v_add_f32_dpp v199, v199, v199 row_half_mirror row_mask:0xf bank_mask:0xf bound_ctrl:1
	v_pk_fma_f32 v[8:9], v[8:9], v[124:125], v[188:189] op_sel:[0,1,0] op_sel_hi:[1,1,1]
	v_add_f32_dpp v198, v198, v198 row_mirror row_mask:0xf bank_mask:0xf bound_ctrl:1
	v_add_f32_dpp v199, v199, v199 row_mirror row_mask:0xf bank_mask:0xf bound_ctrl:1
	v_pk_fma_f32 v[2:3], v[126:127], v[198:199], v[2:3] op_sel:[0,0,0] op_sel_hi:[0,1,1] neg_lo:[0,1,0] neg_hi:[0,1,0]
	v_pk_fma_f32 v[4:5], v[126:127], v[198:199], v[4:5] op_sel:[1,0,0] op_sel_hi:[1,1,1] neg_lo:[0,1,0] neg_hi:[0,1,0]
	v_pk_fma_f32 v[6:7], v[128:129], v[198:199], v[6:7] op_sel:[0,0,0] op_sel_hi:[0,1,1] neg_lo:[0,1,0] neg_hi:[0,1,0]
	v_pk_fma_f32 v[8:9], v[128:129], v[198:199], v[8:9] op_sel:[1,0,0] op_sel_hi:[1,1,1] neg_lo:[0,1,0] neg_hi:[0,1,0]
	v_pk_mul_f32 v[10:11], v[2:3], v[138:139] op_sel:[0,0] op_sel_hi:[1,0]
	v_pk_fma_f32 v[10:11], v[4:5], v[138:139], v[10:11] op_sel:[0,1,0] op_sel_hi:[1,1,1]
	v_pk_fma_f32 v[10:11], v[6:7], v[140:141], v[10:11] op_sel:[0,0,0] op_sel_hi:[1,0,1]
	v_pk_fma_f32 v[10:11], v[8:9], v[140:141], v[10:11] op_sel:[0,1,0] op_sel_hi:[1,1,1]
	s_waitcnt lgkmcnt(0)
	ds_read_b128 v[134:137], v42 offset:28416
	ds_read_b128 v[130:133], v42 offset:28160
	ds_read_b64 v[142:143], v43 offset:27648
	ds_read_b128 v[122:125], v42 offset:27648
	ds_read_b128 v[126:129], v42 offset:27904
	ds_read_b128 v[138:141], v42 offset:28672
	v_pk_mul_f32 v[198:199], v[2:3], v[166:167] op_sel:[0,0] op_sel_hi:[1,0]
	v_pk_mul_f32 v[176:177], v[174:175], v[162:163] op_sel:[0,0] op_sel_hi:[1,0]
	v_pk_fma_f32 v[198:199], v[4:5], v[166:167], v[198:199] op_sel:[0,1,0] op_sel_hi:[1,1,1]
	v_pk_mul_f32 v[178:179], v[174:175], v[162:163] op_sel:[0,1] op_sel_hi:[1,1]
	v_pk_fma_f32 v[198:199], v[6:7], v[168:169], v[198:199] op_sel:[0,0,0] op_sel_hi:[1,0,1]
	v_pk_mul_f32 v[180:181], v[174:175], v[164:165] op_sel:[0,0] op_sel_hi:[1,0]
	v_pk_fma_f32 v[198:199], v[8:9], v[168:169], v[198:199] op_sel:[0,1,0] op_sel_hi:[1,1,1]
	v_pk_mul_f32 v[188:189], v[174:175], v[164:165] op_sel:[0,1] op_sel_hi:[1,1]
	v_pk_fma_f32 v[2:3], v[2:3], v[154:155], v[176:177] op_sel:[0,0,0] op_sel_hi:[1,0,1]
	v_add_f32_dpp v198, v198, v198 quad_perm:[1,0,3,2] row_mask:0xf bank_mask:0xf bound_ctrl:1
	v_add_f32_dpp v199, v199, v199 quad_perm:[1,0,3,2] row_mask:0xf bank_mask:0xf bound_ctrl:1
	v_pk_fma_f32 v[4:5], v[4:5], v[154:155], v[178:179] op_sel:[0,1,0] op_sel_hi:[1,1,1]
	v_add_f32_dpp v198, v198, v198 quad_perm:[2,3,0,1] row_mask:0xf bank_mask:0xf bound_ctrl:1
	v_add_f32_dpp v199, v199, v199 quad_perm:[2,3,0,1] row_mask:0xf bank_mask:0xf bound_ctrl:1
	v_pk_fma_f32 v[6:7], v[6:7], v[156:157], v[180:181] op_sel:[0,0,0] op_sel_hi:[1,0,1]
	v_add_f32_dpp v198, v198, v198 row_half_mirror row_mask:0xf bank_mask:0xf bound_ctrl:1
	v_add_f32_dpp v199, v199, v199 row_half_mirror row_mask:0xf bank_mask:0xf bound_ctrl:1
	v_pk_fma_f32 v[8:9], v[8:9], v[156:157], v[188:189] op_sel:[0,1,0] op_sel_hi:[1,1,1]
	v_add_f32_dpp v198, v198, v198 row_mirror row_mask:0xf bank_mask:0xf bound_ctrl:1
	v_add_f32_dpp v199, v199, v199 row_mirror row_mask:0xf bank_mask:0xf bound_ctrl:1
	v_pk_fma_f32 v[2:3], v[158:159], v[198:199], v[2:3] op_sel:[0,0,0] op_sel_hi:[0,1,1] neg_lo:[0,1,0] neg_hi:[0,1,0]
	v_pk_fma_f32 v[4:5], v[158:159], v[198:199], v[4:5] op_sel:[1,0,0] op_sel_hi:[1,1,1] neg_lo:[0,1,0] neg_hi:[0,1,0]
	v_pk_fma_f32 v[6:7], v[160:161], v[198:199], v[6:7] op_sel:[0,0,0] op_sel_hi:[0,1,1] neg_lo:[0,1,0] neg_hi:[0,1,0]
	v_pk_fma_f32 v[8:9], v[160:161], v[198:199], v[8:9] op_sel:[1,0,0] op_sel_hi:[1,1,1] neg_lo:[0,1,0] neg_hi:[0,1,0]
	v_pk_mul_f32 v[12:13], v[2:3], v[170:171] op_sel:[0,0] op_sel_hi:[1,0]
	v_pk_fma_f32 v[12:13], v[4:5], v[170:171], v[12:13] op_sel:[0,1,0] op_sel_hi:[1,1,1]
	v_pk_fma_f32 v[12:13], v[6:7], v[172:173], v[12:13] op_sel:[0,0,0] op_sel_hi:[1,0,1]
	v_pk_fma_f32 v[12:13], v[8:9], v[172:173], v[12:13] op_sel:[0,1,0] op_sel_hi:[1,1,1]
	s_waitcnt lgkmcnt(0)
	ds_read_b128 v[166:169], v42 offset:29952
	ds_read_b128 v[162:165], v42 offset:29696
	ds_read_b64 v[174:175], v43 offset:29184
	ds_read_b128 v[154:157], v42 offset:29184
	ds_read_b128 v[158:161], v42 offset:29440
	ds_read_b128 v[170:173], v42 offset:30208
	v_pk_mul_f32 v[198:199], v[2:3], v[134:135] op_sel:[0,0] op_sel_hi:[1,0]
	v_pk_mul_f32 v[176:177], v[142:143], v[130:131] op_sel:[0,0] op_sel_hi:[1,0]
	v_pk_fma_f32 v[198:199], v[4:5], v[134:135], v[198:199] op_sel:[0,1,0] op_sel_hi:[1,1,1]
	v_pk_mul_f32 v[178:179], v[142:143], v[130:131] op_sel:[0,1] op_sel_hi:[1,1]
	v_pk_fma_f32 v[198:199], v[6:7], v[136:137], v[198:199] op_sel:[0,0,0] op_sel_hi:[1,0,1]
	v_pk_mul_f32 v[180:181], v[142:143], v[132:133] op_sel:[0,0] op_sel_hi:[1,0]
	v_pk_fma_f32 v[198:199], v[8:9], v[136:137], v[198:199] op_sel:[0,1,0] op_sel_hi:[1,1,1]
	v_pk_mul_f32 v[188:189], v[142:143], v[132:133] op_sel:[0,1] op_sel_hi:[1,1]
	v_pk_fma_f32 v[2:3], v[2:3], v[122:123], v[176:177] op_sel:[0,0,0] op_sel_hi:[1,0,1]
	v_add_f32_dpp v198, v198, v198 quad_perm:[1,0,3,2] row_mask:0xf bank_mask:0xf bound_ctrl:1
	v_add_f32_dpp v199, v199, v199 quad_perm:[1,0,3,2] row_mask:0xf bank_mask:0xf bound_ctrl:1
	v_pk_fma_f32 v[4:5], v[4:5], v[122:123], v[178:179] op_sel:[0,1,0] op_sel_hi:[1,1,1]
	v_add_f32_dpp v198, v198, v198 quad_perm:[2,3,0,1] row_mask:0xf bank_mask:0xf bound_ctrl:1
	v_add_f32_dpp v199, v199, v199 quad_perm:[2,3,0,1] row_mask:0xf bank_mask:0xf bound_ctrl:1
	v_pk_fma_f32 v[6:7], v[6:7], v[124:125], v[180:181] op_sel:[0,0,0] op_sel_hi:[1,0,1]
	v_add_f32_dpp v198, v198, v198 row_half_mirror row_mask:0xf bank_mask:0xf bound_ctrl:1
	v_add_f32_dpp v199, v199, v199 row_half_mirror row_mask:0xf bank_mask:0xf bound_ctrl:1
	v_pk_fma_f32 v[8:9], v[8:9], v[124:125], v[188:189] op_sel:[0,1,0] op_sel_hi:[1,1,1]
	v_add_f32_dpp v198, v198, v198 row_mirror row_mask:0xf bank_mask:0xf bound_ctrl:1
	v_add_f32_dpp v199, v199, v199 row_mirror row_mask:0xf bank_mask:0xf bound_ctrl:1
	v_pk_fma_f32 v[2:3], v[126:127], v[198:199], v[2:3] op_sel:[0,0,0] op_sel_hi:[0,1,1] neg_lo:[0,1,0] neg_hi:[0,1,0]
	v_pk_fma_f32 v[4:5], v[126:127], v[198:199], v[4:5] op_sel:[1,0,0] op_sel_hi:[1,1,1] neg_lo:[0,1,0] neg_hi:[0,1,0]
	v_pk_fma_f32 v[6:7], v[128:129], v[198:199], v[6:7] op_sel:[0,0,0] op_sel_hi:[0,1,1] neg_lo:[0,1,0] neg_hi:[0,1,0]
	v_pk_fma_f32 v[8:9], v[128:129], v[198:199], v[8:9] op_sel:[1,0,0] op_sel_hi:[1,1,1] neg_lo:[0,1,0] neg_hi:[0,1,0]
	v_pk_mul_f32 v[14:15], v[2:3], v[138:139] op_sel:[0,0] op_sel_hi:[1,0]
	v_pk_fma_f32 v[14:15], v[4:5], v[138:139], v[14:15] op_sel:[0,1,0] op_sel_hi:[1,1,1]
	v_pk_fma_f32 v[14:15], v[6:7], v[140:141], v[14:15] op_sel:[0,0,0] op_sel_hi:[1,0,1]
	v_pk_fma_f32 v[14:15], v[8:9], v[140:141], v[14:15] op_sel:[0,1,0] op_sel_hi:[1,1,1]
	s_waitcnt lgkmcnt(0)
	ds_read_b128 v[134:137], v42 offset:31488
	ds_read_b128 v[130:133], v42 offset:31232
	ds_read_b64 v[142:143], v43 offset:30720
	ds_read_b128 v[122:125], v42 offset:30720
	ds_read_b128 v[126:129], v42 offset:30976
	ds_read_b128 v[138:141], v42 offset:31744
	v_pk_mul_f32 v[198:199], v[2:3], v[166:167] op_sel:[0,0] op_sel_hi:[1,0]
	v_pk_mul_f32 v[176:177], v[174:175], v[162:163] op_sel:[0,0] op_sel_hi:[1,0]
	v_pk_fma_f32 v[198:199], v[4:5], v[166:167], v[198:199] op_sel:[0,1,0] op_sel_hi:[1,1,1]
	v_pk_mul_f32 v[178:179], v[174:175], v[162:163] op_sel:[0,1] op_sel_hi:[1,1]
	v_pk_fma_f32 v[198:199], v[6:7], v[168:169], v[198:199] op_sel:[0,0,0] op_sel_hi:[1,0,1]
	v_pk_mul_f32 v[180:181], v[174:175], v[164:165] op_sel:[0,0] op_sel_hi:[1,0]
	v_pk_fma_f32 v[198:199], v[8:9], v[168:169], v[198:199] op_sel:[0,1,0] op_sel_hi:[1,1,1]
	v_pk_mul_f32 v[188:189], v[174:175], v[164:165] op_sel:[0,1] op_sel_hi:[1,1]
	v_pk_fma_f32 v[2:3], v[2:3], v[154:155], v[176:177] op_sel:[0,0,0] op_sel_hi:[1,0,1]
	v_add_f32_dpp v198, v198, v198 quad_perm:[1,0,3,2] row_mask:0xf bank_mask:0xf bound_ctrl:1
	v_add_f32_dpp v199, v199, v199 quad_perm:[1,0,3,2] row_mask:0xf bank_mask:0xf bound_ctrl:1
	v_pk_fma_f32 v[4:5], v[4:5], v[154:155], v[178:179] op_sel:[0,1,0] op_sel_hi:[1,1,1]
	v_add_f32_dpp v198, v198, v198 quad_perm:[2,3,0,1] row_mask:0xf bank_mask:0xf bound_ctrl:1
	v_add_f32_dpp v199, v199, v199 quad_perm:[2,3,0,1] row_mask:0xf bank_mask:0xf bound_ctrl:1
	v_pk_fma_f32 v[6:7], v[6:7], v[156:157], v[180:181] op_sel:[0,0,0] op_sel_hi:[1,0,1]
	v_add_f32_dpp v198, v198, v198 row_half_mirror row_mask:0xf bank_mask:0xf bound_ctrl:1
	v_add_f32_dpp v199, v199, v199 row_half_mirror row_mask:0xf bank_mask:0xf bound_ctrl:1
	v_pk_fma_f32 v[8:9], v[8:9], v[156:157], v[188:189] op_sel:[0,1,0] op_sel_hi:[1,1,1]
	v_add_f32_dpp v198, v198, v198 row_mirror row_mask:0xf bank_mask:0xf bound_ctrl:1
	v_add_f32_dpp v199, v199, v199 row_mirror row_mask:0xf bank_mask:0xf bound_ctrl:1
	v_pk_fma_f32 v[2:3], v[158:159], v[198:199], v[2:3] op_sel:[0,0,0] op_sel_hi:[0,1,1] neg_lo:[0,1,0] neg_hi:[0,1,0]
	v_pk_fma_f32 v[4:5], v[158:159], v[198:199], v[4:5] op_sel:[1,0,0] op_sel_hi:[1,1,1] neg_lo:[0,1,0] neg_hi:[0,1,0]
	v_pk_fma_f32 v[6:7], v[160:161], v[198:199], v[6:7] op_sel:[0,0,0] op_sel_hi:[0,1,1] neg_lo:[0,1,0] neg_hi:[0,1,0]
	v_pk_fma_f32 v[8:9], v[160:161], v[198:199], v[8:9] op_sel:[1,0,0] op_sel_hi:[1,1,1] neg_lo:[0,1,0] neg_hi:[0,1,0]
	v_pk_mul_f32 v[16:17], v[2:3], v[170:171] op_sel:[0,0] op_sel_hi:[1,0]
	v_pk_fma_f32 v[16:17], v[4:5], v[170:171], v[16:17] op_sel:[0,1,0] op_sel_hi:[1,1,1]
	v_pk_fma_f32 v[16:17], v[6:7], v[172:173], v[16:17] op_sel:[0,0,0] op_sel_hi:[1,0,1]
	v_pk_fma_f32 v[16:17], v[8:9], v[172:173], v[16:17] op_sel:[0,1,0] op_sel_hi:[1,1,1]
	s_waitcnt lgkmcnt(0)
	ds_read_b128 v[166:169], v42 offset:33024
	ds_read_b128 v[162:165], v42 offset:32768
	ds_read_b64 v[174:175], v43 offset:32256
	ds_read_b128 v[154:157], v42 offset:32256
	ds_read_b128 v[158:161], v42 offset:32512
	ds_read_b128 v[170:173], v42 offset:33280
	v_pk_mul_f32 v[198:199], v[2:3], v[134:135] op_sel:[0,0] op_sel_hi:[1,0]
	v_pk_mul_f32 v[176:177], v[142:143], v[130:131] op_sel:[0,0] op_sel_hi:[1,0]
	v_pk_fma_f32 v[198:199], v[4:5], v[134:135], v[198:199] op_sel:[0,1,0] op_sel_hi:[1,1,1]
	v_pk_mul_f32 v[178:179], v[142:143], v[130:131] op_sel:[0,1] op_sel_hi:[1,1]
	v_pk_fma_f32 v[198:199], v[6:7], v[136:137], v[198:199] op_sel:[0,0,0] op_sel_hi:[1,0,1]
	v_pk_mul_f32 v[180:181], v[142:143], v[132:133] op_sel:[0,0] op_sel_hi:[1,0]
	v_pk_fma_f32 v[198:199], v[8:9], v[136:137], v[198:199] op_sel:[0,1,0] op_sel_hi:[1,1,1]
	v_pk_mul_f32 v[188:189], v[142:143], v[132:133] op_sel:[0,1] op_sel_hi:[1,1]
	v_pk_fma_f32 v[2:3], v[2:3], v[122:123], v[176:177] op_sel:[0,0,0] op_sel_hi:[1,0,1]
	v_add_f32_dpp v198, v198, v198 quad_perm:[1,0,3,2] row_mask:0xf bank_mask:0xf bound_ctrl:1
	v_add_f32_dpp v199, v199, v199 quad_perm:[1,0,3,2] row_mask:0xf bank_mask:0xf bound_ctrl:1
	v_pk_fma_f32 v[4:5], v[4:5], v[122:123], v[178:179] op_sel:[0,1,0] op_sel_hi:[1,1,1]
	v_add_f32_dpp v198, v198, v198 quad_perm:[2,3,0,1] row_mask:0xf bank_mask:0xf bound_ctrl:1
	v_add_f32_dpp v199, v199, v199 quad_perm:[2,3,0,1] row_mask:0xf bank_mask:0xf bound_ctrl:1
	v_pk_fma_f32 v[6:7], v[6:7], v[124:125], v[180:181] op_sel:[0,0,0] op_sel_hi:[1,0,1]
	v_add_f32_dpp v198, v198, v198 row_half_mirror row_mask:0xf bank_mask:0xf bound_ctrl:1
	v_add_f32_dpp v199, v199, v199 row_half_mirror row_mask:0xf bank_mask:0xf bound_ctrl:1
	v_pk_fma_f32 v[8:9], v[8:9], v[124:125], v[188:189] op_sel:[0,1,0] op_sel_hi:[1,1,1]
	v_add_f32_dpp v198, v198, v198 row_mirror row_mask:0xf bank_mask:0xf bound_ctrl:1
	v_add_f32_dpp v199, v199, v199 row_mirror row_mask:0xf bank_mask:0xf bound_ctrl:1
	v_pk_fma_f32 v[2:3], v[126:127], v[198:199], v[2:3] op_sel:[0,0,0] op_sel_hi:[0,1,1] neg_lo:[0,1,0] neg_hi:[0,1,0]
	v_pk_fma_f32 v[4:5], v[126:127], v[198:199], v[4:5] op_sel:[1,0,0] op_sel_hi:[1,1,1] neg_lo:[0,1,0] neg_hi:[0,1,0]
	v_pk_fma_f32 v[6:7], v[128:129], v[198:199], v[6:7] op_sel:[0,0,0] op_sel_hi:[0,1,1] neg_lo:[0,1,0] neg_hi:[0,1,0]
	v_pk_fma_f32 v[8:9], v[128:129], v[198:199], v[8:9] op_sel:[1,0,0] op_sel_hi:[1,1,1] neg_lo:[0,1,0] neg_hi:[0,1,0]
	v_pk_mul_f32 v[18:19], v[2:3], v[138:139] op_sel:[0,0] op_sel_hi:[1,0]
	v_pk_fma_f32 v[18:19], v[4:5], v[138:139], v[18:19] op_sel:[0,1,0] op_sel_hi:[1,1,1]
	v_pk_fma_f32 v[18:19], v[6:7], v[140:141], v[18:19] op_sel:[0,0,0] op_sel_hi:[1,0,1]
	v_pk_fma_f32 v[18:19], v[8:9], v[140:141], v[18:19] op_sel:[0,1,0] op_sel_hi:[1,1,1]
	s_waitcnt lgkmcnt(0)
	ds_read_b128 v[134:137], v42 offset:34560
	ds_read_b128 v[130:133], v42 offset:34304
	ds_read_b64 v[142:143], v43 offset:33792
	ds_read_b128 v[122:125], v42 offset:33792
	ds_read_b128 v[126:129], v42 offset:34048
	ds_read_b128 v[138:141], v42 offset:34816
	v_pk_mul_f32 v[198:199], v[2:3], v[166:167] op_sel:[0,0] op_sel_hi:[1,0]
	v_pk_mul_f32 v[176:177], v[174:175], v[162:163] op_sel:[0,0] op_sel_hi:[1,0]
	v_pk_fma_f32 v[198:199], v[4:5], v[166:167], v[198:199] op_sel:[0,1,0] op_sel_hi:[1,1,1]
	v_pk_mul_f32 v[178:179], v[174:175], v[162:163] op_sel:[0,1] op_sel_hi:[1,1]
	v_pk_fma_f32 v[198:199], v[6:7], v[168:169], v[198:199] op_sel:[0,0,0] op_sel_hi:[1,0,1]
	v_pk_mul_f32 v[180:181], v[174:175], v[164:165] op_sel:[0,0] op_sel_hi:[1,0]
	v_pk_fma_f32 v[198:199], v[8:9], v[168:169], v[198:199] op_sel:[0,1,0] op_sel_hi:[1,1,1]
	v_pk_mul_f32 v[188:189], v[174:175], v[164:165] op_sel:[0,1] op_sel_hi:[1,1]
	v_pk_fma_f32 v[2:3], v[2:3], v[154:155], v[176:177] op_sel:[0,0,0] op_sel_hi:[1,0,1]
	v_add_f32_dpp v198, v198, v198 quad_perm:[1,0,3,2] row_mask:0xf bank_mask:0xf bound_ctrl:1
	v_add_f32_dpp v199, v199, v199 quad_perm:[1,0,3,2] row_mask:0xf bank_mask:0xf bound_ctrl:1
	v_pk_fma_f32 v[4:5], v[4:5], v[154:155], v[178:179] op_sel:[0,1,0] op_sel_hi:[1,1,1]
	v_add_f32_dpp v198, v198, v198 quad_perm:[2,3,0,1] row_mask:0xf bank_mask:0xf bound_ctrl:1
	v_add_f32_dpp v199, v199, v199 quad_perm:[2,3,0,1] row_mask:0xf bank_mask:0xf bound_ctrl:1
	v_pk_fma_f32 v[6:7], v[6:7], v[156:157], v[180:181] op_sel:[0,0,0] op_sel_hi:[1,0,1]
	v_add_f32_dpp v198, v198, v198 row_half_mirror row_mask:0xf bank_mask:0xf bound_ctrl:1
	v_add_f32_dpp v199, v199, v199 row_half_mirror row_mask:0xf bank_mask:0xf bound_ctrl:1
	v_pk_fma_f32 v[8:9], v[8:9], v[156:157], v[188:189] op_sel:[0,1,0] op_sel_hi:[1,1,1]
	v_add_f32_dpp v198, v198, v198 row_mirror row_mask:0xf bank_mask:0xf bound_ctrl:1
	v_add_f32_dpp v199, v199, v199 row_mirror row_mask:0xf bank_mask:0xf bound_ctrl:1
	v_pk_fma_f32 v[2:3], v[158:159], v[198:199], v[2:3] op_sel:[0,0,0] op_sel_hi:[0,1,1] neg_lo:[0,1,0] neg_hi:[0,1,0]
	v_pk_fma_f32 v[4:5], v[158:159], v[198:199], v[4:5] op_sel:[1,0,0] op_sel_hi:[1,1,1] neg_lo:[0,1,0] neg_hi:[0,1,0]
	v_pk_fma_f32 v[6:7], v[160:161], v[198:199], v[6:7] op_sel:[0,0,0] op_sel_hi:[0,1,1] neg_lo:[0,1,0] neg_hi:[0,1,0]
	v_pk_fma_f32 v[8:9], v[160:161], v[198:199], v[8:9] op_sel:[1,0,0] op_sel_hi:[1,1,1] neg_lo:[0,1,0] neg_hi:[0,1,0]
	v_pk_mul_f32 v[20:21], v[2:3], v[170:171] op_sel:[0,0] op_sel_hi:[1,0]
	v_pk_fma_f32 v[20:21], v[4:5], v[170:171], v[20:21] op_sel:[0,1,0] op_sel_hi:[1,1,1]
	v_pk_fma_f32 v[20:21], v[6:7], v[172:173], v[20:21] op_sel:[0,0,0] op_sel_hi:[1,0,1]
	v_pk_fma_f32 v[20:21], v[8:9], v[172:173], v[20:21] op_sel:[0,1,0] op_sel_hi:[1,1,1]
	s_waitcnt lgkmcnt(0)
	ds_read_b128 v[166:169], v42 offset:36096
	ds_read_b128 v[162:165], v42 offset:35840
	ds_read_b64 v[174:175], v43 offset:35328
	ds_read_b128 v[154:157], v42 offset:35328
	ds_read_b128 v[158:161], v42 offset:35584
	ds_read_b128 v[170:173], v42 offset:36352
	v_pk_mul_f32 v[198:199], v[2:3], v[134:135] op_sel:[0,0] op_sel_hi:[1,0]
	v_pk_mul_f32 v[176:177], v[142:143], v[130:131] op_sel:[0,0] op_sel_hi:[1,0]
	v_pk_fma_f32 v[198:199], v[4:5], v[134:135], v[198:199] op_sel:[0,1,0] op_sel_hi:[1,1,1]
	v_pk_mul_f32 v[178:179], v[142:143], v[130:131] op_sel:[0,1] op_sel_hi:[1,1]
	v_pk_fma_f32 v[198:199], v[6:7], v[136:137], v[198:199] op_sel:[0,0,0] op_sel_hi:[1,0,1]
	v_pk_mul_f32 v[180:181], v[142:143], v[132:133] op_sel:[0,0] op_sel_hi:[1,0]
	v_pk_fma_f32 v[198:199], v[8:9], v[136:137], v[198:199] op_sel:[0,1,0] op_sel_hi:[1,1,1]
	v_pk_mul_f32 v[188:189], v[142:143], v[132:133] op_sel:[0,1] op_sel_hi:[1,1]
	v_pk_fma_f32 v[2:3], v[2:3], v[122:123], v[176:177] op_sel:[0,0,0] op_sel_hi:[1,0,1]
	v_add_f32_dpp v198, v198, v198 quad_perm:[1,0,3,2] row_mask:0xf bank_mask:0xf bound_ctrl:1
	v_add_f32_dpp v199, v199, v199 quad_perm:[1,0,3,2] row_mask:0xf bank_mask:0xf bound_ctrl:1
	v_pk_fma_f32 v[4:5], v[4:5], v[122:123], v[178:179] op_sel:[0,1,0] op_sel_hi:[1,1,1]
	v_add_f32_dpp v198, v198, v198 quad_perm:[2,3,0,1] row_mask:0xf bank_mask:0xf bound_ctrl:1
	v_add_f32_dpp v199, v199, v199 quad_perm:[2,3,0,1] row_mask:0xf bank_mask:0xf bound_ctrl:1
	v_pk_fma_f32 v[6:7], v[6:7], v[124:125], v[180:181] op_sel:[0,0,0] op_sel_hi:[1,0,1]
	v_add_f32_dpp v198, v198, v198 row_half_mirror row_mask:0xf bank_mask:0xf bound_ctrl:1
	v_add_f32_dpp v199, v199, v199 row_half_mirror row_mask:0xf bank_mask:0xf bound_ctrl:1
	v_pk_fma_f32 v[8:9], v[8:9], v[124:125], v[188:189] op_sel:[0,1,0] op_sel_hi:[1,1,1]
	v_add_f32_dpp v198, v198, v198 row_mirror row_mask:0xf bank_mask:0xf bound_ctrl:1
	v_add_f32_dpp v199, v199, v199 row_mirror row_mask:0xf bank_mask:0xf bound_ctrl:1
	v_pk_fma_f32 v[2:3], v[126:127], v[198:199], v[2:3] op_sel:[0,0,0] op_sel_hi:[0,1,1] neg_lo:[0,1,0] neg_hi:[0,1,0]
	v_pk_fma_f32 v[4:5], v[126:127], v[198:199], v[4:5] op_sel:[1,0,0] op_sel_hi:[1,1,1] neg_lo:[0,1,0] neg_hi:[0,1,0]
	v_pk_fma_f32 v[6:7], v[128:129], v[198:199], v[6:7] op_sel:[0,0,0] op_sel_hi:[0,1,1] neg_lo:[0,1,0] neg_hi:[0,1,0]
	v_pk_fma_f32 v[8:9], v[128:129], v[198:199], v[8:9] op_sel:[1,0,0] op_sel_hi:[1,1,1] neg_lo:[0,1,0] neg_hi:[0,1,0]
	v_pk_mul_f32 v[22:23], v[2:3], v[138:139] op_sel:[0,0] op_sel_hi:[1,0]
	v_pk_fma_f32 v[22:23], v[4:5], v[138:139], v[22:23] op_sel:[0,1,0] op_sel_hi:[1,1,1]
	v_pk_fma_f32 v[22:23], v[6:7], v[140:141], v[22:23] op_sel:[0,0,0] op_sel_hi:[1,0,1]
	v_pk_fma_f32 v[22:23], v[8:9], v[140:141], v[22:23] op_sel:[0,1,0] op_sel_hi:[1,1,1]
	s_waitcnt lgkmcnt(0)
	ds_read_b128 v[134:137], v42 offset:37632
	ds_read_b128 v[130:133], v42 offset:37376
	ds_read_b64 v[142:143], v43 offset:36864
	ds_read_b128 v[122:125], v42 offset:36864
	ds_read_b128 v[126:129], v42 offset:37120
	ds_read_b128 v[138:141], v42 offset:37888
	v_pk_mul_f32 v[198:199], v[2:3], v[166:167] op_sel:[0,0] op_sel_hi:[1,0]
	v_pk_mul_f32 v[176:177], v[174:175], v[162:163] op_sel:[0,0] op_sel_hi:[1,0]
	v_pk_fma_f32 v[198:199], v[4:5], v[166:167], v[198:199] op_sel:[0,1,0] op_sel_hi:[1,1,1]
	v_pk_mul_f32 v[178:179], v[174:175], v[162:163] op_sel:[0,1] op_sel_hi:[1,1]
	v_pk_fma_f32 v[198:199], v[6:7], v[168:169], v[198:199] op_sel:[0,0,0] op_sel_hi:[1,0,1]
	v_pk_mul_f32 v[180:181], v[174:175], v[164:165] op_sel:[0,0] op_sel_hi:[1,0]
	v_pk_fma_f32 v[198:199], v[8:9], v[168:169], v[198:199] op_sel:[0,1,0] op_sel_hi:[1,1,1]
	v_pk_mul_f32 v[188:189], v[174:175], v[164:165] op_sel:[0,1] op_sel_hi:[1,1]
	v_pk_fma_f32 v[2:3], v[2:3], v[154:155], v[176:177] op_sel:[0,0,0] op_sel_hi:[1,0,1]
	v_add_f32_dpp v198, v198, v198 quad_perm:[1,0,3,2] row_mask:0xf bank_mask:0xf bound_ctrl:1
	v_add_f32_dpp v199, v199, v199 quad_perm:[1,0,3,2] row_mask:0xf bank_mask:0xf bound_ctrl:1
	v_pk_fma_f32 v[4:5], v[4:5], v[154:155], v[178:179] op_sel:[0,1,0] op_sel_hi:[1,1,1]
	v_add_f32_dpp v198, v198, v198 quad_perm:[2,3,0,1] row_mask:0xf bank_mask:0xf bound_ctrl:1
	v_add_f32_dpp v199, v199, v199 quad_perm:[2,3,0,1] row_mask:0xf bank_mask:0xf bound_ctrl:1
	v_pk_fma_f32 v[6:7], v[6:7], v[156:157], v[180:181] op_sel:[0,0,0] op_sel_hi:[1,0,1]
	v_add_f32_dpp v198, v198, v198 row_half_mirror row_mask:0xf bank_mask:0xf bound_ctrl:1
	v_add_f32_dpp v199, v199, v199 row_half_mirror row_mask:0xf bank_mask:0xf bound_ctrl:1
	v_pk_fma_f32 v[8:9], v[8:9], v[156:157], v[188:189] op_sel:[0,1,0] op_sel_hi:[1,1,1]
	v_add_f32_dpp v198, v198, v198 row_mirror row_mask:0xf bank_mask:0xf bound_ctrl:1
	v_add_f32_dpp v199, v199, v199 row_mirror row_mask:0xf bank_mask:0xf bound_ctrl:1
	v_pk_fma_f32 v[2:3], v[158:159], v[198:199], v[2:3] op_sel:[0,0,0] op_sel_hi:[0,1,1] neg_lo:[0,1,0] neg_hi:[0,1,0]
	v_pk_fma_f32 v[4:5], v[158:159], v[198:199], v[4:5] op_sel:[1,0,0] op_sel_hi:[1,1,1] neg_lo:[0,1,0] neg_hi:[0,1,0]
	v_pk_fma_f32 v[6:7], v[160:161], v[198:199], v[6:7] op_sel:[0,0,0] op_sel_hi:[0,1,1] neg_lo:[0,1,0] neg_hi:[0,1,0]
	v_pk_fma_f32 v[8:9], v[160:161], v[198:199], v[8:9] op_sel:[1,0,0] op_sel_hi:[1,1,1] neg_lo:[0,1,0] neg_hi:[0,1,0]
	v_pk_mul_f32 v[24:25], v[2:3], v[170:171] op_sel:[0,0] op_sel_hi:[1,0]
	v_pk_fma_f32 v[24:25], v[4:5], v[170:171], v[24:25] op_sel:[0,1,0] op_sel_hi:[1,1,1]
	v_pk_fma_f32 v[24:25], v[6:7], v[172:173], v[24:25] op_sel:[0,0,0] op_sel_hi:[1,0,1]
	v_pk_fma_f32 v[24:25], v[8:9], v[172:173], v[24:25] op_sel:[0,1,0] op_sel_hi:[1,1,1]
	s_waitcnt lgkmcnt(0)
	ds_read_b128 v[166:169], v42 offset:39168
	ds_read_b128 v[162:165], v42 offset:38912
	ds_read_b64 v[174:175], v43 offset:38400
	ds_read_b128 v[154:157], v42 offset:38400
	ds_read_b128 v[158:161], v42 offset:38656
	ds_read_b128 v[170:173], v42 offset:39424
	v_pk_mul_f32 v[198:199], v[2:3], v[134:135] op_sel:[0,0] op_sel_hi:[1,0]
	v_pk_mul_f32 v[176:177], v[142:143], v[130:131] op_sel:[0,0] op_sel_hi:[1,0]
	v_pk_fma_f32 v[198:199], v[4:5], v[134:135], v[198:199] op_sel:[0,1,0] op_sel_hi:[1,1,1]
	v_pk_mul_f32 v[178:179], v[142:143], v[130:131] op_sel:[0,1] op_sel_hi:[1,1]
	v_pk_fma_f32 v[198:199], v[6:7], v[136:137], v[198:199] op_sel:[0,0,0] op_sel_hi:[1,0,1]
	v_pk_mul_f32 v[180:181], v[142:143], v[132:133] op_sel:[0,0] op_sel_hi:[1,0]
	v_pk_fma_f32 v[198:199], v[8:9], v[136:137], v[198:199] op_sel:[0,1,0] op_sel_hi:[1,1,1]
	v_pk_mul_f32 v[188:189], v[142:143], v[132:133] op_sel:[0,1] op_sel_hi:[1,1]
	v_pk_fma_f32 v[2:3], v[2:3], v[122:123], v[176:177] op_sel:[0,0,0] op_sel_hi:[1,0,1]
	v_add_f32_dpp v198, v198, v198 quad_perm:[1,0,3,2] row_mask:0xf bank_mask:0xf bound_ctrl:1
	v_add_f32_dpp v199, v199, v199 quad_perm:[1,0,3,2] row_mask:0xf bank_mask:0xf bound_ctrl:1
	v_pk_fma_f32 v[4:5], v[4:5], v[122:123], v[178:179] op_sel:[0,1,0] op_sel_hi:[1,1,1]
	v_add_f32_dpp v198, v198, v198 quad_perm:[2,3,0,1] row_mask:0xf bank_mask:0xf bound_ctrl:1
	v_add_f32_dpp v199, v199, v199 quad_perm:[2,3,0,1] row_mask:0xf bank_mask:0xf bound_ctrl:1
	v_pk_fma_f32 v[6:7], v[6:7], v[124:125], v[180:181] op_sel:[0,0,0] op_sel_hi:[1,0,1]
	v_add_f32_dpp v198, v198, v198 row_half_mirror row_mask:0xf bank_mask:0xf bound_ctrl:1
	v_add_f32_dpp v199, v199, v199 row_half_mirror row_mask:0xf bank_mask:0xf bound_ctrl:1
	v_pk_fma_f32 v[8:9], v[8:9], v[124:125], v[188:189] op_sel:[0,1,0] op_sel_hi:[1,1,1]
	v_add_f32_dpp v198, v198, v198 row_mirror row_mask:0xf bank_mask:0xf bound_ctrl:1
	v_add_f32_dpp v199, v199, v199 row_mirror row_mask:0xf bank_mask:0xf bound_ctrl:1
	v_pk_fma_f32 v[2:3], v[126:127], v[198:199], v[2:3] op_sel:[0,0,0] op_sel_hi:[0,1,1] neg_lo:[0,1,0] neg_hi:[0,1,0]
	v_pk_fma_f32 v[4:5], v[126:127], v[198:199], v[4:5] op_sel:[1,0,0] op_sel_hi:[1,1,1] neg_lo:[0,1,0] neg_hi:[0,1,0]
	v_pk_fma_f32 v[6:7], v[128:129], v[198:199], v[6:7] op_sel:[0,0,0] op_sel_hi:[0,1,1] neg_lo:[0,1,0] neg_hi:[0,1,0]
	v_pk_fma_f32 v[8:9], v[128:129], v[198:199], v[8:9] op_sel:[1,0,0] op_sel_hi:[1,1,1] neg_lo:[0,1,0] neg_hi:[0,1,0]
	v_pk_mul_f32 v[26:27], v[2:3], v[138:139] op_sel:[0,0] op_sel_hi:[1,0]
	v_pk_fma_f32 v[26:27], v[4:5], v[138:139], v[26:27] op_sel:[0,1,0] op_sel_hi:[1,1,1]
	v_pk_fma_f32 v[26:27], v[6:7], v[140:141], v[26:27] op_sel:[0,0,0] op_sel_hi:[1,0,1]
	v_pk_fma_f32 v[26:27], v[8:9], v[140:141], v[26:27] op_sel:[0,1,0] op_sel_hi:[1,1,1]
	s_waitcnt lgkmcnt(0)
	ds_read_b128 v[134:137], v42 offset:40704
	ds_read_b128 v[130:133], v42 offset:40448
	ds_read_b64 v[142:143], v43 offset:39936
	ds_read_b128 v[122:125], v42 offset:39936
	ds_read_b128 v[126:129], v42 offset:40192
	ds_read_b128 v[138:141], v42 offset:40960
	v_pk_mul_f32 v[198:199], v[2:3], v[166:167] op_sel:[0,0] op_sel_hi:[1,0]
	v_pk_mul_f32 v[176:177], v[174:175], v[162:163] op_sel:[0,0] op_sel_hi:[1,0]
	v_pk_fma_f32 v[198:199], v[4:5], v[166:167], v[198:199] op_sel:[0,1,0] op_sel_hi:[1,1,1]
	v_pk_mul_f32 v[178:179], v[174:175], v[162:163] op_sel:[0,1] op_sel_hi:[1,1]
	v_pk_fma_f32 v[198:199], v[6:7], v[168:169], v[198:199] op_sel:[0,0,0] op_sel_hi:[1,0,1]
	v_pk_mul_f32 v[180:181], v[174:175], v[164:165] op_sel:[0,0] op_sel_hi:[1,0]
	v_pk_fma_f32 v[198:199], v[8:9], v[168:169], v[198:199] op_sel:[0,1,0] op_sel_hi:[1,1,1]
	v_pk_mul_f32 v[188:189], v[174:175], v[164:165] op_sel:[0,1] op_sel_hi:[1,1]
	v_pk_fma_f32 v[2:3], v[2:3], v[154:155], v[176:177] op_sel:[0,0,0] op_sel_hi:[1,0,1]
	v_add_f32_dpp v198, v198, v198 quad_perm:[1,0,3,2] row_mask:0xf bank_mask:0xf bound_ctrl:1
	v_add_f32_dpp v199, v199, v199 quad_perm:[1,0,3,2] row_mask:0xf bank_mask:0xf bound_ctrl:1
	v_pk_fma_f32 v[4:5], v[4:5], v[154:155], v[178:179] op_sel:[0,1,0] op_sel_hi:[1,1,1]
	v_add_f32_dpp v198, v198, v198 quad_perm:[2,3,0,1] row_mask:0xf bank_mask:0xf bound_ctrl:1
	v_add_f32_dpp v199, v199, v199 quad_perm:[2,3,0,1] row_mask:0xf bank_mask:0xf bound_ctrl:1
	v_pk_fma_f32 v[6:7], v[6:7], v[156:157], v[180:181] op_sel:[0,0,0] op_sel_hi:[1,0,1]
	v_add_f32_dpp v198, v198, v198 row_half_mirror row_mask:0xf bank_mask:0xf bound_ctrl:1
	v_add_f32_dpp v199, v199, v199 row_half_mirror row_mask:0xf bank_mask:0xf bound_ctrl:1
	v_pk_fma_f32 v[8:9], v[8:9], v[156:157], v[188:189] op_sel:[0,1,0] op_sel_hi:[1,1,1]
	v_add_f32_dpp v198, v198, v198 row_mirror row_mask:0xf bank_mask:0xf bound_ctrl:1
	v_add_f32_dpp v199, v199, v199 row_mirror row_mask:0xf bank_mask:0xf bound_ctrl:1
	v_pk_fma_f32 v[2:3], v[158:159], v[198:199], v[2:3] op_sel:[0,0,0] op_sel_hi:[0,1,1] neg_lo:[0,1,0] neg_hi:[0,1,0]
	v_pk_fma_f32 v[4:5], v[158:159], v[198:199], v[4:5] op_sel:[1,0,0] op_sel_hi:[1,1,1] neg_lo:[0,1,0] neg_hi:[0,1,0]
	v_pk_fma_f32 v[6:7], v[160:161], v[198:199], v[6:7] op_sel:[0,0,0] op_sel_hi:[0,1,1] neg_lo:[0,1,0] neg_hi:[0,1,0]
	v_pk_fma_f32 v[8:9], v[160:161], v[198:199], v[8:9] op_sel:[1,0,0] op_sel_hi:[1,1,1] neg_lo:[0,1,0] neg_hi:[0,1,0]
	v_pk_mul_f32 v[28:29], v[2:3], v[170:171] op_sel:[0,0] op_sel_hi:[1,0]
	v_pk_fma_f32 v[28:29], v[4:5], v[170:171], v[28:29] op_sel:[0,1,0] op_sel_hi:[1,1,1]
	v_pk_fma_f32 v[28:29], v[6:7], v[172:173], v[28:29] op_sel:[0,0,0] op_sel_hi:[1,0,1]
	v_pk_fma_f32 v[28:29], v[8:9], v[172:173], v[28:29] op_sel:[0,1,0] op_sel_hi:[1,1,1]
	s_waitcnt lgkmcnt(0)
	ds_read_b128 v[166:169], v42 offset:42240
	ds_read_b128 v[162:165], v42 offset:41984
	ds_read_b64 v[174:175], v43 offset:41472
	ds_read_b128 v[154:157], v42 offset:41472
	ds_read_b128 v[158:161], v42 offset:41728
	ds_read_b128 v[170:173], v42 offset:42496
	v_pk_mul_f32 v[198:199], v[2:3], v[134:135] op_sel:[0,0] op_sel_hi:[1,0]
	v_pk_mul_f32 v[176:177], v[142:143], v[130:131] op_sel:[0,0] op_sel_hi:[1,0]
	v_pk_fma_f32 v[198:199], v[4:5], v[134:135], v[198:199] op_sel:[0,1,0] op_sel_hi:[1,1,1]
	v_pk_mul_f32 v[178:179], v[142:143], v[130:131] op_sel:[0,1] op_sel_hi:[1,1]
	v_pk_fma_f32 v[198:199], v[6:7], v[136:137], v[198:199] op_sel:[0,0,0] op_sel_hi:[1,0,1]
	v_pk_mul_f32 v[180:181], v[142:143], v[132:133] op_sel:[0,0] op_sel_hi:[1,0]
	v_pk_fma_f32 v[198:199], v[8:9], v[136:137], v[198:199] op_sel:[0,1,0] op_sel_hi:[1,1,1]
	v_pk_mul_f32 v[188:189], v[142:143], v[132:133] op_sel:[0,1] op_sel_hi:[1,1]
	v_pk_fma_f32 v[2:3], v[2:3], v[122:123], v[176:177] op_sel:[0,0,0] op_sel_hi:[1,0,1]
	v_add_f32_dpp v198, v198, v198 quad_perm:[1,0,3,2] row_mask:0xf bank_mask:0xf bound_ctrl:1
	v_add_f32_dpp v199, v199, v199 quad_perm:[1,0,3,2] row_mask:0xf bank_mask:0xf bound_ctrl:1
	v_pk_fma_f32 v[4:5], v[4:5], v[122:123], v[178:179] op_sel:[0,1,0] op_sel_hi:[1,1,1]
	v_add_f32_dpp v198, v198, v198 quad_perm:[2,3,0,1] row_mask:0xf bank_mask:0xf bound_ctrl:1
	v_add_f32_dpp v199, v199, v199 quad_perm:[2,3,0,1] row_mask:0xf bank_mask:0xf bound_ctrl:1
	v_pk_fma_f32 v[6:7], v[6:7], v[124:125], v[180:181] op_sel:[0,0,0] op_sel_hi:[1,0,1]
	v_add_f32_dpp v198, v198, v198 row_half_mirror row_mask:0xf bank_mask:0xf bound_ctrl:1
	v_add_f32_dpp v199, v199, v199 row_half_mirror row_mask:0xf bank_mask:0xf bound_ctrl:1
	v_pk_fma_f32 v[8:9], v[8:9], v[124:125], v[188:189] op_sel:[0,1,0] op_sel_hi:[1,1,1]
	v_add_f32_dpp v198, v198, v198 row_mirror row_mask:0xf bank_mask:0xf bound_ctrl:1
	v_add_f32_dpp v199, v199, v199 row_mirror row_mask:0xf bank_mask:0xf bound_ctrl:1
	v_pk_fma_f32 v[2:3], v[126:127], v[198:199], v[2:3] op_sel:[0,0,0] op_sel_hi:[0,1,1] neg_lo:[0,1,0] neg_hi:[0,1,0]
	v_pk_fma_f32 v[4:5], v[126:127], v[198:199], v[4:5] op_sel:[1,0,0] op_sel_hi:[1,1,1] neg_lo:[0,1,0] neg_hi:[0,1,0]
	v_pk_fma_f32 v[6:7], v[128:129], v[198:199], v[6:7] op_sel:[0,0,0] op_sel_hi:[0,1,1] neg_lo:[0,1,0] neg_hi:[0,1,0]
	v_pk_fma_f32 v[8:9], v[128:129], v[198:199], v[8:9] op_sel:[1,0,0] op_sel_hi:[1,1,1] neg_lo:[0,1,0] neg_hi:[0,1,0]
	v_pk_mul_f32 v[30:31], v[2:3], v[138:139] op_sel:[0,0] op_sel_hi:[1,0]
	v_pk_fma_f32 v[30:31], v[4:5], v[138:139], v[30:31] op_sel:[0,1,0] op_sel_hi:[1,1,1]
	v_pk_fma_f32 v[30:31], v[6:7], v[140:141], v[30:31] op_sel:[0,0,0] op_sel_hi:[1,0,1]
	v_pk_fma_f32 v[30:31], v[8:9], v[140:141], v[30:31] op_sel:[0,1,0] op_sel_hi:[1,1,1]
	s_waitcnt lgkmcnt(0)
	ds_read_b128 v[134:137], v42 offset:43776
	ds_read_b128 v[130:133], v42 offset:43520
	ds_read_b64 v[142:143], v43 offset:43008
	ds_read_b128 v[122:125], v42 offset:43008
	ds_read_b128 v[126:129], v42 offset:43264
	ds_read_b128 v[138:141], v42 offset:44032
	v_pk_mul_f32 v[198:199], v[2:3], v[166:167] op_sel:[0,0] op_sel_hi:[1,0]
	v_pk_mul_f32 v[176:177], v[174:175], v[162:163] op_sel:[0,0] op_sel_hi:[1,0]
	v_pk_fma_f32 v[198:199], v[4:5], v[166:167], v[198:199] op_sel:[0,1,0] op_sel_hi:[1,1,1]
	v_pk_mul_f32 v[178:179], v[174:175], v[162:163] op_sel:[0,1] op_sel_hi:[1,1]
	v_pk_fma_f32 v[198:199], v[6:7], v[168:169], v[198:199] op_sel:[0,0,0] op_sel_hi:[1,0,1]
	v_pk_mul_f32 v[180:181], v[174:175], v[164:165] op_sel:[0,0] op_sel_hi:[1,0]
	v_pk_fma_f32 v[198:199], v[8:9], v[168:169], v[198:199] op_sel:[0,1,0] op_sel_hi:[1,1,1]
	v_pk_mul_f32 v[188:189], v[174:175], v[164:165] op_sel:[0,1] op_sel_hi:[1,1]
	v_pk_fma_f32 v[2:3], v[2:3], v[154:155], v[176:177] op_sel:[0,0,0] op_sel_hi:[1,0,1]
	v_add_f32_dpp v198, v198, v198 quad_perm:[1,0,3,2] row_mask:0xf bank_mask:0xf bound_ctrl:1
	v_add_f32_dpp v199, v199, v199 quad_perm:[1,0,3,2] row_mask:0xf bank_mask:0xf bound_ctrl:1
	v_pk_fma_f32 v[4:5], v[4:5], v[154:155], v[178:179] op_sel:[0,1,0] op_sel_hi:[1,1,1]
	v_add_f32_dpp v198, v198, v198 quad_perm:[2,3,0,1] row_mask:0xf bank_mask:0xf bound_ctrl:1
	v_add_f32_dpp v199, v199, v199 quad_perm:[2,3,0,1] row_mask:0xf bank_mask:0xf bound_ctrl:1
	v_pk_fma_f32 v[6:7], v[6:7], v[156:157], v[180:181] op_sel:[0,0,0] op_sel_hi:[1,0,1]
	v_add_f32_dpp v198, v198, v198 row_half_mirror row_mask:0xf bank_mask:0xf bound_ctrl:1
	v_add_f32_dpp v199, v199, v199 row_half_mirror row_mask:0xf bank_mask:0xf bound_ctrl:1
	v_pk_fma_f32 v[8:9], v[8:9], v[156:157], v[188:189] op_sel:[0,1,0] op_sel_hi:[1,1,1]
	v_add_f32_dpp v198, v198, v198 row_mirror row_mask:0xf bank_mask:0xf bound_ctrl:1
	v_add_f32_dpp v199, v199, v199 row_mirror row_mask:0xf bank_mask:0xf bound_ctrl:1
	v_pk_fma_f32 v[2:3], v[158:159], v[198:199], v[2:3] op_sel:[0,0,0] op_sel_hi:[0,1,1] neg_lo:[0,1,0] neg_hi:[0,1,0]
	v_pk_fma_f32 v[4:5], v[158:159], v[198:199], v[4:5] op_sel:[1,0,0] op_sel_hi:[1,1,1] neg_lo:[0,1,0] neg_hi:[0,1,0]
	v_pk_fma_f32 v[6:7], v[160:161], v[198:199], v[6:7] op_sel:[0,0,0] op_sel_hi:[0,1,1] neg_lo:[0,1,0] neg_hi:[0,1,0]
	v_pk_fma_f32 v[8:9], v[160:161], v[198:199], v[8:9] op_sel:[1,0,0] op_sel_hi:[1,1,1] neg_lo:[0,1,0] neg_hi:[0,1,0]
	v_pk_mul_f32 v[32:33], v[2:3], v[170:171] op_sel:[0,0] op_sel_hi:[1,0]
	v_pk_fma_f32 v[32:33], v[4:5], v[170:171], v[32:33] op_sel:[0,1,0] op_sel_hi:[1,1,1]
	v_pk_fma_f32 v[32:33], v[6:7], v[172:173], v[32:33] op_sel:[0,0,0] op_sel_hi:[1,0,1]
	v_pk_fma_f32 v[32:33], v[8:9], v[172:173], v[32:33] op_sel:[0,1,0] op_sel_hi:[1,1,1]
	s_waitcnt lgkmcnt(0)
	ds_read_b128 v[166:169], v42 offset:45312
	ds_read_b128 v[162:165], v42 offset:45056
	ds_read_b64 v[174:175], v43 offset:44544
	ds_read_b128 v[154:157], v42 offset:44544
	ds_read_b128 v[158:161], v42 offset:44800
	ds_read_b128 v[170:173], v42 offset:45568
	v_pk_mul_f32 v[198:199], v[2:3], v[134:135] op_sel:[0,0] op_sel_hi:[1,0]
	v_pk_mul_f32 v[176:177], v[142:143], v[130:131] op_sel:[0,0] op_sel_hi:[1,0]
	v_pk_fma_f32 v[198:199], v[4:5], v[134:135], v[198:199] op_sel:[0,1,0] op_sel_hi:[1,1,1]
	v_pk_mul_f32 v[178:179], v[142:143], v[130:131] op_sel:[0,1] op_sel_hi:[1,1]
	v_pk_fma_f32 v[198:199], v[6:7], v[136:137], v[198:199] op_sel:[0,0,0] op_sel_hi:[1,0,1]
	v_pk_mul_f32 v[180:181], v[142:143], v[132:133] op_sel:[0,0] op_sel_hi:[1,0]
	v_pk_fma_f32 v[198:199], v[8:9], v[136:137], v[198:199] op_sel:[0,1,0] op_sel_hi:[1,1,1]
	v_pk_mul_f32 v[188:189], v[142:143], v[132:133] op_sel:[0,1] op_sel_hi:[1,1]
	v_pk_fma_f32 v[2:3], v[2:3], v[122:123], v[176:177] op_sel:[0,0,0] op_sel_hi:[1,0,1]
	v_add_f32_dpp v198, v198, v198 quad_perm:[1,0,3,2] row_mask:0xf bank_mask:0xf bound_ctrl:1
	v_add_f32_dpp v199, v199, v199 quad_perm:[1,0,3,2] row_mask:0xf bank_mask:0xf bound_ctrl:1
	v_pk_fma_f32 v[4:5], v[4:5], v[122:123], v[178:179] op_sel:[0,1,0] op_sel_hi:[1,1,1]
	v_add_f32_dpp v198, v198, v198 quad_perm:[2,3,0,1] row_mask:0xf bank_mask:0xf bound_ctrl:1
	v_add_f32_dpp v199, v199, v199 quad_perm:[2,3,0,1] row_mask:0xf bank_mask:0xf bound_ctrl:1
	v_pk_fma_f32 v[6:7], v[6:7], v[124:125], v[180:181] op_sel:[0,0,0] op_sel_hi:[1,0,1]
	v_add_f32_dpp v198, v198, v198 row_half_mirror row_mask:0xf bank_mask:0xf bound_ctrl:1
	v_add_f32_dpp v199, v199, v199 row_half_mirror row_mask:0xf bank_mask:0xf bound_ctrl:1
	v_pk_fma_f32 v[8:9], v[8:9], v[124:125], v[188:189] op_sel:[0,1,0] op_sel_hi:[1,1,1]
	v_add_f32_dpp v198, v198, v198 row_mirror row_mask:0xf bank_mask:0xf bound_ctrl:1
	v_add_f32_dpp v199, v199, v199 row_mirror row_mask:0xf bank_mask:0xf bound_ctrl:1
	v_pk_fma_f32 v[2:3], v[126:127], v[198:199], v[2:3] op_sel:[0,0,0] op_sel_hi:[0,1,1] neg_lo:[0,1,0] neg_hi:[0,1,0]
	v_pk_fma_f32 v[4:5], v[126:127], v[198:199], v[4:5] op_sel:[1,0,0] op_sel_hi:[1,1,1] neg_lo:[0,1,0] neg_hi:[0,1,0]
	v_pk_fma_f32 v[6:7], v[128:129], v[198:199], v[6:7] op_sel:[0,0,0] op_sel_hi:[0,1,1] neg_lo:[0,1,0] neg_hi:[0,1,0]
	v_pk_fma_f32 v[8:9], v[128:129], v[198:199], v[8:9] op_sel:[1,0,0] op_sel_hi:[1,1,1] neg_lo:[0,1,0] neg_hi:[0,1,0]
	v_pk_mul_f32 v[34:35], v[2:3], v[138:139] op_sel:[0,0] op_sel_hi:[1,0]
	v_pk_fma_f32 v[34:35], v[4:5], v[138:139], v[34:35] op_sel:[0,1,0] op_sel_hi:[1,1,1]
	v_pk_fma_f32 v[34:35], v[6:7], v[140:141], v[34:35] op_sel:[0,0,0] op_sel_hi:[1,0,1]
	v_pk_fma_f32 v[34:35], v[8:9], v[140:141], v[34:35] op_sel:[0,1,0] op_sel_hi:[1,1,1]
	s_waitcnt lgkmcnt(0)
	ds_read_b128 v[134:137], v42 offset:46848
	ds_read_b128 v[130:133], v42 offset:46592
	ds_read_b64 v[142:143], v43 offset:46080
	ds_read_b128 v[122:125], v42 offset:46080
	ds_read_b128 v[126:129], v42 offset:46336
	ds_read_b128 v[138:141], v42 offset:47104
	v_pk_mul_f32 v[198:199], v[2:3], v[166:167] op_sel:[0,0] op_sel_hi:[1,0]
	v_pk_mul_f32 v[176:177], v[174:175], v[162:163] op_sel:[0,0] op_sel_hi:[1,0]
	v_pk_fma_f32 v[198:199], v[4:5], v[166:167], v[198:199] op_sel:[0,1,0] op_sel_hi:[1,1,1]
	v_pk_mul_f32 v[178:179], v[174:175], v[162:163] op_sel:[0,1] op_sel_hi:[1,1]
	v_pk_fma_f32 v[198:199], v[6:7], v[168:169], v[198:199] op_sel:[0,0,0] op_sel_hi:[1,0,1]
	v_pk_mul_f32 v[180:181], v[174:175], v[164:165] op_sel:[0,0] op_sel_hi:[1,0]
	v_pk_fma_f32 v[198:199], v[8:9], v[168:169], v[198:199] op_sel:[0,1,0] op_sel_hi:[1,1,1]
	v_pk_mul_f32 v[188:189], v[174:175], v[164:165] op_sel:[0,1] op_sel_hi:[1,1]
	v_pk_fma_f32 v[2:3], v[2:3], v[154:155], v[176:177] op_sel:[0,0,0] op_sel_hi:[1,0,1]
	v_add_f32_dpp v198, v198, v198 quad_perm:[1,0,3,2] row_mask:0xf bank_mask:0xf bound_ctrl:1
	v_add_f32_dpp v199, v199, v199 quad_perm:[1,0,3,2] row_mask:0xf bank_mask:0xf bound_ctrl:1
	v_pk_fma_f32 v[4:5], v[4:5], v[154:155], v[178:179] op_sel:[0,1,0] op_sel_hi:[1,1,1]
	v_add_f32_dpp v198, v198, v198 quad_perm:[2,3,0,1] row_mask:0xf bank_mask:0xf bound_ctrl:1
	v_add_f32_dpp v199, v199, v199 quad_perm:[2,3,0,1] row_mask:0xf bank_mask:0xf bound_ctrl:1
	v_pk_fma_f32 v[6:7], v[6:7], v[156:157], v[180:181] op_sel:[0,0,0] op_sel_hi:[1,0,1]
	v_add_f32_dpp v198, v198, v198 row_half_mirror row_mask:0xf bank_mask:0xf bound_ctrl:1
	v_add_f32_dpp v199, v199, v199 row_half_mirror row_mask:0xf bank_mask:0xf bound_ctrl:1
	v_pk_fma_f32 v[8:9], v[8:9], v[156:157], v[188:189] op_sel:[0,1,0] op_sel_hi:[1,1,1]
	v_add_f32_dpp v198, v198, v198 row_mirror row_mask:0xf bank_mask:0xf bound_ctrl:1
	v_add_f32_dpp v199, v199, v199 row_mirror row_mask:0xf bank_mask:0xf bound_ctrl:1
	v_pk_fma_f32 v[2:3], v[158:159], v[198:199], v[2:3] op_sel:[0,0,0] op_sel_hi:[0,1,1] neg_lo:[0,1,0] neg_hi:[0,1,0]
	v_pk_fma_f32 v[4:5], v[158:159], v[198:199], v[4:5] op_sel:[1,0,0] op_sel_hi:[1,1,1] neg_lo:[0,1,0] neg_hi:[0,1,0]
	v_pk_fma_f32 v[6:7], v[160:161], v[198:199], v[6:7] op_sel:[0,0,0] op_sel_hi:[0,1,1] neg_lo:[0,1,0] neg_hi:[0,1,0]
	v_pk_fma_f32 v[8:9], v[160:161], v[198:199], v[8:9] op_sel:[1,0,0] op_sel_hi:[1,1,1] neg_lo:[0,1,0] neg_hi:[0,1,0]
	v_pk_mul_f32 v[36:37], v[2:3], v[170:171] op_sel:[0,0] op_sel_hi:[1,0]
	v_pk_fma_f32 v[36:37], v[4:5], v[170:171], v[36:37] op_sel:[0,1,0] op_sel_hi:[1,1,1]
	v_pk_fma_f32 v[36:37], v[6:7], v[172:173], v[36:37] op_sel:[0,0,0] op_sel_hi:[1,0,1]
	v_pk_fma_f32 v[36:37], v[8:9], v[172:173], v[36:37] op_sel:[0,1,0] op_sel_hi:[1,1,1]
	s_waitcnt lgkmcnt(0)
	ds_read_b128 v[166:169], v42 offset:48384
	ds_read_b128 v[162:165], v42 offset:48128
	ds_read_b64 v[174:175], v43 offset:47616
	ds_read_b128 v[154:157], v42 offset:47616
	ds_read_b128 v[158:161], v42 offset:47872
	ds_read_b128 v[170:173], v42 offset:48640
	v_pk_mul_f32 v[198:199], v[2:3], v[134:135] op_sel:[0,0] op_sel_hi:[1,0]
	v_pk_mul_f32 v[176:177], v[142:143], v[130:131] op_sel:[0,0] op_sel_hi:[1,0]
	v_pk_fma_f32 v[198:199], v[4:5], v[134:135], v[198:199] op_sel:[0,1,0] op_sel_hi:[1,1,1]
	v_pk_mul_f32 v[178:179], v[142:143], v[130:131] op_sel:[0,1] op_sel_hi:[1,1]
	v_pk_fma_f32 v[198:199], v[6:7], v[136:137], v[198:199] op_sel:[0,0,0] op_sel_hi:[1,0,1]
	v_pk_mul_f32 v[180:181], v[142:143], v[132:133] op_sel:[0,0] op_sel_hi:[1,0]
	v_pk_fma_f32 v[198:199], v[8:9], v[136:137], v[198:199] op_sel:[0,1,0] op_sel_hi:[1,1,1]
	v_pk_mul_f32 v[188:189], v[142:143], v[132:133] op_sel:[0,1] op_sel_hi:[1,1]
	v_pk_fma_f32 v[2:3], v[2:3], v[122:123], v[176:177] op_sel:[0,0,0] op_sel_hi:[1,0,1]
	v_add_f32_dpp v198, v198, v198 quad_perm:[1,0,3,2] row_mask:0xf bank_mask:0xf bound_ctrl:1
	v_add_f32_dpp v199, v199, v199 quad_perm:[1,0,3,2] row_mask:0xf bank_mask:0xf bound_ctrl:1
	v_pk_fma_f32 v[4:5], v[4:5], v[122:123], v[178:179] op_sel:[0,1,0] op_sel_hi:[1,1,1]
	v_add_f32_dpp v198, v198, v198 quad_perm:[2,3,0,1] row_mask:0xf bank_mask:0xf bound_ctrl:1
	v_add_f32_dpp v199, v199, v199 quad_perm:[2,3,0,1] row_mask:0xf bank_mask:0xf bound_ctrl:1
	v_pk_fma_f32 v[6:7], v[6:7], v[124:125], v[180:181] op_sel:[0,0,0] op_sel_hi:[1,0,1]
	v_add_f32_dpp v198, v198, v198 row_half_mirror row_mask:0xf bank_mask:0xf bound_ctrl:1
	v_add_f32_dpp v199, v199, v199 row_half_mirror row_mask:0xf bank_mask:0xf bound_ctrl:1
	v_pk_fma_f32 v[8:9], v[8:9], v[124:125], v[188:189] op_sel:[0,1,0] op_sel_hi:[1,1,1]
	v_add_f32_dpp v198, v198, v198 row_mirror row_mask:0xf bank_mask:0xf bound_ctrl:1
	v_add_f32_dpp v199, v199, v199 row_mirror row_mask:0xf bank_mask:0xf bound_ctrl:1
	v_pk_fma_f32 v[2:3], v[126:127], v[198:199], v[2:3] op_sel:[0,0,0] op_sel_hi:[0,1,1] neg_lo:[0,1,0] neg_hi:[0,1,0]
	v_pk_fma_f32 v[4:5], v[126:127], v[198:199], v[4:5] op_sel:[1,0,0] op_sel_hi:[1,1,1] neg_lo:[0,1,0] neg_hi:[0,1,0]
	v_pk_fma_f32 v[6:7], v[128:129], v[198:199], v[6:7] op_sel:[0,0,0] op_sel_hi:[0,1,1] neg_lo:[0,1,0] neg_hi:[0,1,0]
	v_pk_fma_f32 v[8:9], v[128:129], v[198:199], v[8:9] op_sel:[1,0,0] op_sel_hi:[1,1,1] neg_lo:[0,1,0] neg_hi:[0,1,0]
	v_pk_mul_f32 v[38:39], v[2:3], v[138:139] op_sel:[0,0] op_sel_hi:[1,0]
	v_pk_fma_f32 v[38:39], v[4:5], v[138:139], v[38:39] op_sel:[0,1,0] op_sel_hi:[1,1,1]
	v_pk_fma_f32 v[38:39], v[6:7], v[140:141], v[38:39] op_sel:[0,0,0] op_sel_hi:[1,0,1]
	v_pk_fma_f32 v[38:39], v[8:9], v[140:141], v[38:39] op_sel:[0,1,0] op_sel_hi:[1,1,1]
	s_waitcnt lgkmcnt(0)
	v_pk_mul_f32 v[198:199], v[2:3], v[166:167] op_sel:[0,0] op_sel_hi:[1,0]
	v_pk_mul_f32 v[176:177], v[174:175], v[162:163] op_sel:[0,0] op_sel_hi:[1,0]
	v_pk_fma_f32 v[198:199], v[4:5], v[166:167], v[198:199] op_sel:[0,1,0] op_sel_hi:[1,1,1]
	v_pk_mul_f32 v[178:179], v[174:175], v[162:163] op_sel:[0,1] op_sel_hi:[1,1]
	v_pk_fma_f32 v[198:199], v[6:7], v[168:169], v[198:199] op_sel:[0,0,0] op_sel_hi:[1,0,1]
	v_pk_mul_f32 v[180:181], v[174:175], v[164:165] op_sel:[0,0] op_sel_hi:[1,0]
	v_pk_fma_f32 v[198:199], v[8:9], v[168:169], v[198:199] op_sel:[0,1,0] op_sel_hi:[1,1,1]
	v_pk_mul_f32 v[188:189], v[174:175], v[164:165] op_sel:[0,1] op_sel_hi:[1,1]
	v_pk_fma_f32 v[2:3], v[2:3], v[154:155], v[176:177] op_sel:[0,0,0] op_sel_hi:[1,0,1]
	v_add_f32_dpp v198, v198, v198 quad_perm:[1,0,3,2] row_mask:0xf bank_mask:0xf bound_ctrl:1
	v_add_f32_dpp v199, v199, v199 quad_perm:[1,0,3,2] row_mask:0xf bank_mask:0xf bound_ctrl:1
	v_pk_fma_f32 v[4:5], v[4:5], v[154:155], v[178:179] op_sel:[0,1,0] op_sel_hi:[1,1,1]
	v_add_f32_dpp v198, v198, v198 quad_perm:[2,3,0,1] row_mask:0xf bank_mask:0xf bound_ctrl:1
	v_add_f32_dpp v199, v199, v199 quad_perm:[2,3,0,1] row_mask:0xf bank_mask:0xf bound_ctrl:1
	v_pk_fma_f32 v[6:7], v[6:7], v[156:157], v[180:181] op_sel:[0,0,0] op_sel_hi:[1,0,1]
	v_add_f32_dpp v198, v198, v198 row_half_mirror row_mask:0xf bank_mask:0xf bound_ctrl:1
	v_add_f32_dpp v199, v199, v199 row_half_mirror row_mask:0xf bank_mask:0xf bound_ctrl:1
	v_pk_fma_f32 v[8:9], v[8:9], v[156:157], v[188:189] op_sel:[0,1,0] op_sel_hi:[1,1,1]
	v_add_f32_dpp v198, v198, v198 row_mirror row_mask:0xf bank_mask:0xf bound_ctrl:1
	v_add_f32_dpp v199, v199, v199 row_mirror row_mask:0xf bank_mask:0xf bound_ctrl:1
	v_pk_fma_f32 v[2:3], v[158:159], v[198:199], v[2:3] op_sel:[0,0,0] op_sel_hi:[0,1,1] neg_lo:[0,1,0] neg_hi:[0,1,0]
	v_pk_fma_f32 v[4:5], v[158:159], v[198:199], v[4:5] op_sel:[1,0,0] op_sel_hi:[1,1,1] neg_lo:[0,1,0] neg_hi:[0,1,0]
	v_pk_fma_f32 v[6:7], v[160:161], v[198:199], v[6:7] op_sel:[0,0,0] op_sel_hi:[0,1,1] neg_lo:[0,1,0] neg_hi:[0,1,0]
	v_pk_fma_f32 v[8:9], v[160:161], v[198:199], v[8:9] op_sel:[1,0,0] op_sel_hi:[1,1,1] neg_lo:[0,1,0] neg_hi:[0,1,0]
	v_pk_mul_f32 v[40:41], v[2:3], v[170:171] op_sel:[0,0] op_sel_hi:[1,0]
	v_pk_fma_f32 v[40:41], v[4:5], v[170:171], v[40:41] op_sel:[0,1,0] op_sel_hi:[1,1,1]
	v_pk_fma_f32 v[40:41], v[6:7], v[172:173], v[40:41] op_sel:[0,0,0] op_sel_hi:[1,0,1]
	v_pk_fma_f32 v[40:41], v[8:9], v[172:173], v[40:41] op_sel:[0,1,0] op_sel_hi:[1,1,1]
	v_add_f32_dpp v190, v10, v10 row_mirror row_mask:0xf bank_mask:0x3
	v_add_f32_dpp v190, v26, v26 row_mirror row_mask:0xf bank_mask:0xc
	v_add_f32_dpp v191, v12, v12 row_mirror row_mask:0xf bank_mask:0x3
	v_add_f32_dpp v191, v28, v28 row_mirror row_mask:0xf bank_mask:0xc
	v_add_f32_dpp v192, v14, v14 row_mirror row_mask:0xf bank_mask:0x3
	v_add_f32_dpp v192, v30, v30 row_mirror row_mask:0xf bank_mask:0xc
	v_add_f32_dpp v193, v16, v16 row_mirror row_mask:0xf bank_mask:0x3
	v_add_f32_dpp v193, v32, v32 row_mirror row_mask:0xf bank_mask:0xc
	v_add_f32_dpp v194, v18, v18 row_mirror row_mask:0xf bank_mask:0x3
	v_add_f32_dpp v194, v34, v34 row_mirror row_mask:0xf bank_mask:0xc
	v_add_f32_dpp v195, v20, v20 row_mirror row_mask:0xf bank_mask:0x3
	v_add_f32_dpp v195, v36, v36 row_mirror row_mask:0xf bank_mask:0xc
	v_add_f32_dpp v196, v22, v22 row_mirror row_mask:0xf bank_mask:0x3
	v_add_f32_dpp v196, v38, v38 row_mirror row_mask:0xf bank_mask:0xc
	v_add_f32_dpp v197, v24, v24 row_mirror row_mask:0xf bank_mask:0x3
	v_add_f32_dpp v197, v40, v40 row_mirror row_mask:0xf bank_mask:0xc
	v_add_f32_dpp v202, v190, v190 row_half_mirror row_mask:0xf bank_mask:0x5
	v_add_f32_dpp v202, v194, v194 row_half_mirror row_mask:0xf bank_mask:0xa
	v_add_f32_dpp v203, v191, v191 row_half_mirror row_mask:0xf bank_mask:0x5
	v_add_f32_dpp v203, v195, v195 row_half_mirror row_mask:0xf bank_mask:0xa
	v_add_f32_dpp v204, v192, v192 row_half_mirror row_mask:0xf bank_mask:0x5
	v_add_f32_dpp v204, v196, v196 row_half_mirror row_mask:0xf bank_mask:0xa
	v_add_f32_dpp v205, v193, v193 row_half_mirror row_mask:0xf bank_mask:0x5
	v_add_f32_dpp v205, v197, v197 row_half_mirror row_mask:0xf bank_mask:0xa
	v_cndmask_b32_e64 v176, v202, v204, s[84:85]
	v_cndmask_b32_e64 v177, v204, v202, s[84:85]
	v_cndmask_b32_e64 v178, v203, v205, s[84:85]
	v_cndmask_b32_e64 v179, v205, v203, s[84:85]
	s_nop 1
	v_add_f32_dpp v210, v177, v176 quad_perm:[2,3,0,1] row_mask:0xf bank_mask:0xf bound_ctrl:1
	v_add_f32_dpp v211, v179, v178 quad_perm:[2,3,0,1] row_mask:0xf bank_mask:0xf bound_ctrl:1
	s_nop 0
	v_cndmask_b32_e64 v176, v210, v211, s[88:89]
	v_cndmask_b32_e64 v177, v211, v210, s[88:89]
	s_nop 1
	v_add_f32_dpp v212, v177, v176 quad_perm:[1,0,3,2] row_mask:0xf bank_mask:0xf bound_ctrl:1
	ds_write_b32 v44, v212 offset:2304
	v_add_f32_dpp v190, v11, v11 row_mirror row_mask:0xf bank_mask:0x3
	v_add_f32_dpp v190, v27, v27 row_mirror row_mask:0xf bank_mask:0xc
	v_add_f32_dpp v191, v13, v13 row_mirror row_mask:0xf bank_mask:0x3
	v_add_f32_dpp v191, v29, v29 row_mirror row_mask:0xf bank_mask:0xc
	v_add_f32_dpp v192, v15, v15 row_mirror row_mask:0xf bank_mask:0x3
	v_add_f32_dpp v192, v31, v31 row_mirror row_mask:0xf bank_mask:0xc
	v_add_f32_dpp v193, v17, v17 row_mirror row_mask:0xf bank_mask:0x3
	v_add_f32_dpp v193, v33, v33 row_mirror row_mask:0xf bank_mask:0xc
	v_add_f32_dpp v194, v19, v19 row_mirror row_mask:0xf bank_mask:0x3
	v_add_f32_dpp v194, v35, v35 row_mirror row_mask:0xf bank_mask:0xc
	v_add_f32_dpp v195, v21, v21 row_mirror row_mask:0xf bank_mask:0x3
	v_add_f32_dpp v195, v37, v37 row_mirror row_mask:0xf bank_mask:0xc
	v_add_f32_dpp v196, v23, v23 row_mirror row_mask:0xf bank_mask:0x3
	v_add_f32_dpp v196, v39, v39 row_mirror row_mask:0xf bank_mask:0xc
	v_add_f32_dpp v197, v25, v25 row_mirror row_mask:0xf bank_mask:0x3
	v_add_f32_dpp v197, v41, v41 row_mirror row_mask:0xf bank_mask:0xc
	v_add_f32_dpp v202, v190, v190 row_half_mirror row_mask:0xf bank_mask:0x5
	v_add_f32_dpp v202, v194, v194 row_half_mirror row_mask:0xf bank_mask:0xa
	v_add_f32_dpp v203, v191, v191 row_half_mirror row_mask:0xf bank_mask:0x5
	v_add_f32_dpp v203, v195, v195 row_half_mirror row_mask:0xf bank_mask:0xa
	v_add_f32_dpp v204, v192, v192 row_half_mirror row_mask:0xf bank_mask:0x5
	v_add_f32_dpp v204, v196, v196 row_half_mirror row_mask:0xf bank_mask:0xa
	v_add_f32_dpp v205, v193, v193 row_half_mirror row_mask:0xf bank_mask:0x5
	v_add_f32_dpp v205, v197, v197 row_half_mirror row_mask:0xf bank_mask:0xa
	v_cndmask_b32_e64 v176, v202, v204, s[84:85]
	v_cndmask_b32_e64 v177, v204, v202, s[84:85]
	v_cndmask_b32_e64 v178, v203, v205, s[84:85]
	v_cndmask_b32_e64 v179, v205, v203, s[84:85]
	s_nop 1
	v_add_f32_dpp v210, v177, v176 quad_perm:[2,3,0,1] row_mask:0xf bank_mask:0xf bound_ctrl:1
	v_add_f32_dpp v211, v179, v178 quad_perm:[2,3,0,1] row_mask:0xf bank_mask:0xf bound_ctrl:1
	s_nop 0
	v_cndmask_b32_e64 v176, v210, v211, s[88:89]
	v_cndmask_b32_e64 v177, v211, v210, s[88:89]
	s_nop 1
	v_add_f32_dpp v212, v177, v176 quad_perm:[1,0,3,2] row_mask:0xf bank_mask:0xf bound_ctrl:1
	ds_write_b32 v44, v212 offset:2308
	v_xor_b32_e32 v42, 0xc000, v42
	v_xor_b32_e32 v43, 0xc000, v43
	v_xor_b32_e32 v44, 0x2000, v44
	s_branch .Lrc_join
